# first-iteration peel and counted first wait extended to the four LoRA-up GEMM loops (trampoline for one out-of-range branch)
# speedup vs baseline: 1.0043x; 1.0043x over previous
; #define PG8_STAGE(bufoff, gbase, voff) do { _Pragma("unroll") for (int _i = 0; _i < 2; ++_i) \
;         __builtin_amdgcn_global_load_lds((const unsigned*)((const char*)(gbase) + (voff)[_i]), (LAS unsigned*)(lds + (bufoff) + ldsw + _i * 8192), 16, 0, 0); } while (0)
; #define PG8_LDA(dst, b, h) do { _Pragma("unroll") for (int m = 0; m < 4; ++m) _Pragma("unroll") for (int k = 0; k < 2; ++k) dst[m][k] = *(const LAS h16x8*)(lds + PG8_SA(b, h) + aoff + m * 2048 + k * 1024); } while (0)
; #define PG8_LDB(dst, b, h) do { _Pragma("unroll") for (int n = 0; n < 2; ++n) _Pragma("unroll") for (int k = 0; k < 2; ++k) dst[n][k] = *(const LAS h16x8*)(lds + PG8_SB(b, h) + boff + n * 2048 + k * 1024); } while (0)
; #define PG8_MMA(ai, bj, At, Bt_) do { __builtin_amdgcn_s_setprio(1); _Pragma("unroll") for (int m = 0; m < 4; ++m) _Pragma("unroll") for (int n = 0; n < 2; ++n) _Pragma("unroll") for (int k = 0; k < 2; ++k) \
;         acc[ai][bj][m][n] = __builtin_amdgcn_mfma_f32_16x16x32_f16(Bt_[n][k], At[m][k], acc[ai][bj][m][n], 0, 0, 0); __builtin_amdgcn_s_setprio(0); } while (0)
; template <class Epi, class AMap>
; __device__ __forceinline__ void gemm_phase(LAS unsigned char* lds, const AMap am, const int lda, const h16* Bt, const int ldb, const int M, const int N, const int K, const Epi& E) {
;     ...
;         const bool has_next = S.next(ui + 1, nxt);
;         const char* nA = has_next ? am(nxt.pn) + (size_t)nxt.pm * tstepA : cA; const char* nB = has_next ? (const char*)Bt + (size_t)nxt.pn * tstepB : cB;
; #pragma unroll 1
;         for (int t = 0; t < nt; t += 2) {
;             const bool last = (t == nt - 2);
;             const char* a1 = cA + (size_t)(t + 1) * kstep;
;             const char* a2 = last ? nA : cA + (size_t)(t + 2) * kstep; const char* b2 = last ? nB : cB + (size_t)(t + 2) * kstep;
;             const char* a3 = a2 + kstep; const char* b3 = b2 + kstep;
;             PG8_LDB(B0, 0, 0); PG8_SCHED; PG8_LDA(At, 0, 0); PG8_STAGE(PG8_SA(1, 1), a1 + hstepA, voffA);
;             PG8_WAIT_L(8); PG8_BAR; PG8_WAIT_L(0); PG8_MMA(0, 0, At, B0); PG8_BAR; PG8_SCHED;
;             PG8_LDB(B1, 0, 1); PG8_STAGE(PG8_SB(0, 0), b2, voffB);
;             PG8_BAR; PG8_WAIT_L(0); PG8_MMA(0, 1, At, B1); PG8_BAR;
;             PG8_LDA(At, 0, 1); PG8_STAGE(PG8_SA(0, 0), a2, voffA);
;             PG8_BAR; PG8_WAIT_L(0); PG8_MMA(1, 0, At, B0); PG8_BAR; PG8_SCHED;
.Lg4p_621:
	s_add_i32 s51, s26, 2
	s_add_u32 s0, s22, 0x100
	s_addc_u32 s1, s23, 0
	s_add_i32 s60, 0, 0x10000
	v_add_u32_e32 v152, s60, v155
	ds_read_b128 v[90:93], v152
	ds_read_b128 v[94:97], v152 offset:1024
	ds_read_b128 v[148:151], v152 offset:2048
	ds_read_b128 v[158:161], v152 offset:3072
	s_cmp_eq_u32 s82, s26
	s_cselect_b32 s26, s21, s29
	s_cselect_b32 s49, s65, s1
	s_cselect_b32 s48, s64, s0
	s_cselect_b32 s27, s20, s45
	v_lshl_add_u64 v[152:153], s[22:23], 0, v[144:145]
	s_add_i32 m0, s76, 0xc000
	ds_read_b128 v[162:165], v157
	ds_read_b128 v[166:169], v157 offset:1024
	ds_read_b128 v[170:173], v157 offset:2048
	ds_read_b128 v[174:177], v157 offset:3072
	ds_read_b128 v[178:181], v157 offset:4096
	ds_read_b128 v[182:185], v157 offset:5120
	ds_read_b128 v[186:189], v157 offset:6144
	ds_read_b128 v[190:193], v157 offset:7168
	global_load_lds_dwordx4 v[152:153], off
	v_lshl_add_u64 v[152:153], s[22:23], 0, v[146:147]
	s_add_i32 m0, s76, 0xe000
	s_nop 0
	global_load_lds_dwordx4 v[152:153], off
	s_waitcnt lgkmcnt(11)
	s_add_i32 s62, 0, 0x14000
	v_add_u32_e32 v152, s62, v155
	s_add_i32 s22, s60, s73
	ds_read_b128 v[194:197], v152
	ds_read_b128 v[198:201], v152 offset:1024
	ds_read_b128 v[202:205], v152 offset:2048
	ds_read_b128 v[220:223], v152 offset:3072
	s_waitcnt vmcnt(28) lgkmcnt(0)
	s_barrier
	v_mfma_f32_16x16x32_f16 v[130:133], v[90:93], v[162:165], 0
	v_mfma_f32_16x16x32_f16 v[134:137], v[148:151], v[162:165], 0
	v_mfma_f32_16x16x32_f16 v[126:129], v[90:93], v[170:173], 0
	v_mfma_f32_16x16x32_f16 v[122:125], v[148:151], v[170:173], 0
	v_mfma_f32_16x16x32_f16 v[118:121], v[90:93], v[178:181], 0
	v_mfma_f32_16x16x32_f16 v[114:117], v[148:151], v[178:181], 0
	v_mfma_f32_16x16x32_f16 v[110:113], v[90:93], v[186:189], 0
	v_mfma_f32_16x16x32_f16 v[106:109], v[148:151], v[186:189], 0
	v_mfma_f32_16x16x32_f16 v[130:133], v[94:97], v[166:169], v[130:133]
	v_mfma_f32_16x16x32_f16 v[134:137], v[158:161], v[166:169], v[134:137]
	v_mfma_f32_16x16x32_f16 v[126:129], v[94:97], v[174:177], v[126:129]
	v_mfma_f32_16x16x32_f16 v[122:125], v[158:161], v[174:177], v[122:125]
	v_mfma_f32_16x16x32_f16 v[118:121], v[94:97], v[182:185], v[118:121]
	v_mfma_f32_16x16x32_f16 v[114:117], v[158:161], v[182:185], v[114:117]
	v_mfma_f32_16x16x32_f16 v[110:113], v[94:97], v[190:193], v[110:113]
	v_mfma_f32_16x16x32_f16 v[106:109], v[158:161], v[190:193], v[106:109]
	v_mfma_f32_16x16x32_f16 v[62:65], v[194:197], v[162:165], 0
	v_mfma_f32_16x16x32_f16 v[58:61], v[202:205], v[162:165], 0
	v_mfma_f32_16x16x32_f16 v[54:57], v[194:197], v[170:173], 0
	v_mfma_f32_16x16x32_f16 v[50:53], v[202:205], v[170:173], 0
	v_mfma_f32_16x16x32_f16 v[46:49], v[194:197], v[178:181], 0
	v_mfma_f32_16x16x32_f16 v[42:45], v[202:205], v[178:181], 0
	v_mfma_f32_16x16x32_f16 v[38:41], v[194:197], v[186:189], 0
	v_mfma_f32_16x16x32_f16 v[34:37], v[202:205], v[186:189], 0
	v_mfma_f32_16x16x32_f16 v[62:65], v[198:201], v[166:169], v[62:65]
	v_mfma_f32_16x16x32_f16 v[58:61], v[220:223], v[166:169], v[58:61]
	v_mfma_f32_16x16x32_f16 v[54:57], v[198:201], v[174:177], v[54:57]
	v_mfma_f32_16x16x32_f16 v[50:53], v[220:223], v[174:177], v[50:53]
	v_mfma_f32_16x16x32_f16 v[46:49], v[198:201], v[182:185], v[46:49]
	v_mfma_f32_16x16x32_f16 v[42:45], v[220:223], v[182:185], v[42:45]
	v_mfma_f32_16x16x32_f16 v[38:41], v[198:201], v[190:193], v[38:41]
	v_mfma_f32_16x16x32_f16 v[34:37], v[220:223], v[190:193], v[34:37]
	s_barrier
	v_lshl_add_u64 v[152:153], s[26:27], 0, v[0:1]
	s_mov_b32 m0, s22
	v_lshl_add_u64 v[206:207], s[26:27], 0, v[142:143]
	global_load_lds_dwordx4 v[152:153], off
	s_add_i32 m0, s22, 0x2000
	s_nop 0
	global_load_lds_dwordx4 v[206:207], off
	s_mov_b32 m0, s76
	v_lshl_add_u64 v[212:213], s[48:49], 0, v[138:139]
	ds_read_b128 v[162:165], v157 offset:16384
	ds_read_b128 v[166:169], v157 offset:17408
	ds_read_b128 v[170:173], v157 offset:18432
	ds_read_b128 v[174:177], v157 offset:19456
	ds_read_b128 v[178:181], v157 offset:20480
	ds_read_b128 v[182:185], v157 offset:21504
	ds_read_b128 v[186:189], v157 offset:22528
	ds_read_b128 v[190:193], v157 offset:23552
	global_load_lds_dwordx4 v[212:213], off
	v_lshl_add_u64 v[224:225], s[48:49], 0, v[140:141]
	s_mov_b32 m0, s77
	s_nop 0
	global_load_lds_dwordx4 v[224:225], off
	s_add_u32 s22, s26, 0x10000
	s_addc_u32 s23, s27, 0
	s_add_i32 s60, s62, s73
	v_lshl_add_u64 v[232:233], s[22:23], 0, v[0:1]
	s_mov_b32 m0, s60
	s_nop 0
	global_load_lds_dwordx4 v[232:233], off
	v_lshl_add_u64 v[232:233], s[22:23], 0, v[142:143]
	s_add_i32 m0, s60, 0x2000
	s_nop 0
	global_load_lds_dwordx4 v[232:233], off
	s_waitcnt vmcnt(8) lgkmcnt(0)
	s_barrier
; #define PG8_STAGE(bufoff, gbase, voff) do { _Pragma("unroll") for (int _i = 0; _i < 2; ++_i) \
;         __builtin_amdgcn_global_load_lds((const unsigned*)((const char*)(gbase) + (voff)[_i]), (LAS unsigned*)(lds + (bufoff) + ldsw + _i * 8192), 16, 0, 0); } while (0)
; #define PG8_LDA(dst, b, h) do { _Pragma("unroll") for (int m = 0; m < 4; ++m) _Pragma("unroll") for (int k = 0; k < 2; ++k) dst[m][k] = *(const LAS h16x8*)(lds + PG8_SA(b, h) + aoff + m * 2048 + k * 1024); } while (0)
; #define PG8_LDB(dst, b, h) do { _Pragma("unroll") for (int n = 0; n < 2; ++n) _Pragma("unroll") for (int k = 0; k < 2; ++k) dst[n][k] = *(const LAS h16x8*)(lds + PG8_SB(b, h) + boff + n * 2048 + k * 1024); } while (0)
; #define PG8_MMA(ai, bj, At, Bt_) do { __builtin_amdgcn_s_setprio(1); _Pragma("unroll") for (int m = 0; m < 4; ++m) _Pragma("unroll") for (int n = 0; n < 2; ++n) _Pragma("unroll") for (int k = 0; k < 2; ++k) \
;         acc[ai][bj][m][n] = __builtin_amdgcn_mfma_f32_16x16x32_f16(Bt_[n][k], At[m][k], acc[ai][bj][m][n], 0, 0, 0); __builtin_amdgcn_s_setprio(0); } while (0)
; #define PG8_WAIT_V(n) asm volatile("s_waitcnt vmcnt(" #n ")" ::: "memory")
; #define PG8_WAIT_L(n) asm volatile("s_waitcnt lgkmcnt(" #n ")" ::: "memory")
; #define PG8_BAR __builtin_amdgcn_s_barrier()
; #define PG8_SCHED __builtin_amdgcn_sched_barrier(0)
; template <class Epi, class AMap>
; __device__ __forceinline__ void gemm_phase(LAS unsigned char* lds, const AMap am, const int lda, const h16* Bt, const int ldb, const int M, const int N, const int K, const Epi& E) {
;     ...
;             PG8_BAR; PG8_WAIT_L(0); PG8_MMA(1, 0, At, B0); PG8_BAR; PG8_SCHED;
;             PG8_STAGE(PG8_SB(0, 1), b2 + hstepB, voffB);
;             PG8_WAIT_V(6); PG8_BAR; PG8_MMA(1, 1, At, B1); PG8_BAR;
;             PG8_LDB(B0, 1, 0); PG8_SCHED; PG8_LDA(At, 1, 0); PG8_STAGE(PG8_SA(0, 1), a2 + hstepA, voffA);
;             PG8_WAIT_L(8); PG8_BAR; PG8_WAIT_L(0); PG8_MMA(0, 0, At, B0); PG8_BAR; PG8_SCHED;
;             PG8_LDB(B1, 1, 1); PG8_STAGE(PG8_SB(1, 0), b3, voffB);
;             PG8_BAR; PG8_WAIT_L(0); PG8_MMA(0, 1, At, B1); PG8_BAR;
	v_mfma_f32_16x16x32_f16 v[102:105], v[90:93], v[162:165], 0
	v_mfma_f32_16x16x32_f16 v[98:101], v[148:151], v[162:165], 0
	v_mfma_f32_16x16x32_f16 v[86:89], v[90:93], v[170:173], 0
	v_mfma_f32_16x16x32_f16 v[82:85], v[148:151], v[170:173], 0
	v_mfma_f32_16x16x32_f16 v[78:81], v[90:93], v[178:181], 0
	v_mfma_f32_16x16x32_f16 v[74:77], v[148:151], v[178:181], 0
	v_mfma_f32_16x16x32_f16 v[70:73], v[90:93], v[186:189], 0
	v_mfma_f32_16x16x32_f16 v[66:69], v[148:151], v[186:189], 0
	v_mfma_f32_16x16x32_f16 v[102:105], v[94:97], v[166:169], v[102:105]
	v_mfma_f32_16x16x32_f16 v[98:101], v[158:161], v[166:169], v[98:101]
	v_mfma_f32_16x16x32_f16 v[86:89], v[94:97], v[174:177], v[86:89]
	v_mfma_f32_16x16x32_f16 v[82:85], v[158:161], v[174:177], v[82:85]
	v_mfma_f32_16x16x32_f16 v[78:81], v[94:97], v[182:185], v[78:81]
	v_mfma_f32_16x16x32_f16 v[74:77], v[158:161], v[182:185], v[74:77]
	v_mfma_f32_16x16x32_f16 v[70:73], v[94:97], v[190:193], v[70:73]
	v_mfma_f32_16x16x32_f16 v[66:69], v[158:161], v[190:193], v[66:69]
	v_mfma_f32_16x16x32_f16 v[30:33], v[194:197], v[162:165], 0
	v_mfma_f32_16x16x32_f16 v[26:29], v[202:205], v[162:165], 0
	v_mfma_f32_16x16x32_f16 v[22:25], v[194:197], v[170:173], 0
	v_mfma_f32_16x16x32_f16 v[18:21], v[202:205], v[170:173], 0
	v_mfma_f32_16x16x32_f16 v[14:17], v[194:197], v[178:181], 0
	v_mfma_f32_16x16x32_f16 v[10:13], v[202:205], v[178:181], 0
	v_mfma_f32_16x16x32_f16 v[6:9], v[194:197], v[186:189], 0
	v_mfma_f32_16x16x32_f16 v[2:5], v[202:205], v[186:189], 0
	v_mfma_f32_16x16x32_f16 v[30:33], v[198:201], v[166:169], v[30:33]
	v_mfma_f32_16x16x32_f16 v[26:29], v[220:223], v[166:169], v[26:29]
	v_mfma_f32_16x16x32_f16 v[22:25], v[198:201], v[174:177], v[22:25]
	v_mfma_f32_16x16x32_f16 v[18:21], v[220:223], v[174:177], v[18:21]
	v_mfma_f32_16x16x32_f16 v[14:17], v[198:201], v[182:185], v[14:17]
	v_mfma_f32_16x16x32_f16 v[10:13], v[220:223], v[182:185], v[10:13]
	v_mfma_f32_16x16x32_f16 v[6:9], v[198:201], v[190:193], v[6:9]
	v_mfma_f32_16x16x32_f16 v[2:5], v[220:223], v[190:193], v[2:5]
	s_barrier
	s_add_i32 s60, 0, 0x18000
	v_add_u32_e32 v234, s60, v155
	ds_read_b128 v[90:93], v234
	ds_read_b128 v[94:97], v234 offset:1024
	ds_read_b128 v[148:151], v234 offset:2048
	ds_read_b128 v[158:161], v234 offset:3072
	s_add_u32 s22, s48, 0x1c0000
	s_addc_u32 s23, s49, 0
	s_mov_b32 m0, s78
	v_lshl_add_u64 v[232:233], s[22:23], 0, v[138:139]
	ds_read_b128 v[162:165], v157 offset:32768
	ds_read_b128 v[166:169], v157 offset:33792
	ds_read_b128 v[170:173], v157 offset:34816
	ds_read_b128 v[174:177], v157 offset:35840
	ds_read_b128 v[178:181], v157 offset:36864
	ds_read_b128 v[182:185], v157 offset:37888
	ds_read_b128 v[186:189], v157 offset:38912
	ds_read_b128 v[190:193], v157 offset:39936
	global_load_lds_dwordx4 v[232:233], off
	v_lshl_add_u64 v[232:233], s[22:23], 0, v[140:141]
	s_mov_b32 m0, s79
	s_nop 0
	global_load_lds_dwordx4 v[232:233], off
	s_waitcnt lgkmcnt(11)
	s_add_i32 s48, 0, 0x1c000
	s_add_i32 s22, s60, s73
	v_add_u32_e32 v214, s48, v155
	v_lshl_add_u64 v[152:153], v[152:153], 0, s[92:93]
	s_mov_b32 m0, s22
	ds_read_b128 v[194:197], v214
	ds_read_b128 v[198:201], v214 offset:1024
	ds_read_b128 v[202:205], v214 offset:2048
	ds_read_b128 v[220:223], v214 offset:3072
	s_waitcnt vmcnt(8) lgkmcnt(0)
	s_barrier
	v_mfma_f32_16x16x32_f16 v[130:133], v[90:93], v[162:165], v[130:133]
	v_mfma_f32_16x16x32_f16 v[134:137], v[148:151], v[162:165], v[134:137]
	v_mfma_f32_16x16x32_f16 v[126:129], v[90:93], v[170:173], v[126:129]
	v_mfma_f32_16x16x32_f16 v[122:125], v[148:151], v[170:173], v[122:125]
	v_mfma_f32_16x16x32_f16 v[118:121], v[90:93], v[178:181], v[118:121]
	v_mfma_f32_16x16x32_f16 v[114:117], v[148:151], v[178:181], v[114:117]
	v_mfma_f32_16x16x32_f16 v[110:113], v[90:93], v[186:189], v[110:113]
	v_mfma_f32_16x16x32_f16 v[106:109], v[148:151], v[186:189], v[106:109]
	v_mfma_f32_16x16x32_f16 v[130:133], v[94:97], v[166:169], v[130:133]
	v_mfma_f32_16x16x32_f16 v[134:137], v[158:161], v[166:169], v[134:137]
	v_mfma_f32_16x16x32_f16 v[126:129], v[94:97], v[174:177], v[126:129]
	v_mfma_f32_16x16x32_f16 v[122:125], v[158:161], v[174:177], v[122:125]
	v_mfma_f32_16x16x32_f16 v[118:121], v[94:97], v[182:185], v[118:121]
	v_mfma_f32_16x16x32_f16 v[114:117], v[158:161], v[182:185], v[114:117]
	v_mfma_f32_16x16x32_f16 v[110:113], v[94:97], v[190:193], v[110:113]
	v_mfma_f32_16x16x32_f16 v[106:109], v[158:161], v[190:193], v[106:109]
	v_mfma_f32_16x16x32_f16 v[62:65], v[194:197], v[162:165], v[62:65]
	v_mfma_f32_16x16x32_f16 v[58:61], v[202:205], v[162:165], v[58:61]
	v_mfma_f32_16x16x32_f16 v[54:57], v[194:197], v[170:173], v[54:57]
	v_mfma_f32_16x16x32_f16 v[50:53], v[202:205], v[170:173], v[50:53]
	v_mfma_f32_16x16x32_f16 v[46:49], v[194:197], v[178:181], v[46:49]
	v_mfma_f32_16x16x32_f16 v[42:45], v[202:205], v[178:181], v[42:45]
	v_mfma_f32_16x16x32_f16 v[38:41], v[194:197], v[186:189], v[38:41]
	v_mfma_f32_16x16x32_f16 v[34:37], v[202:205], v[186:189], v[34:37]
	v_mfma_f32_16x16x32_f16 v[62:65], v[198:201], v[166:169], v[62:65]
	v_mfma_f32_16x16x32_f16 v[58:61], v[220:223], v[166:169], v[58:61]
	v_mfma_f32_16x16x32_f16 v[54:57], v[198:201], v[174:177], v[54:57]
	v_mfma_f32_16x16x32_f16 v[50:53], v[220:223], v[174:177], v[50:53]
	v_mfma_f32_16x16x32_f16 v[46:49], v[198:201], v[182:185], v[46:49]
	v_mfma_f32_16x16x32_f16 v[42:45], v[220:223], v[182:185], v[42:45]
	v_mfma_f32_16x16x32_f16 v[38:41], v[198:201], v[190:193], v[38:41]
	v_mfma_f32_16x16x32_f16 v[34:37], v[220:223], v[190:193], v[34:37]
	s_barrier
; #define PG8_STAGE(bufoff, gbase, voff) do { _Pragma("unroll") for (int _i = 0; _i < 2; ++_i) \
;         __builtin_amdgcn_global_load_lds((const unsigned*)((const char*)(gbase) + (voff)[_i]), (LAS unsigned*)(lds + (bufoff) + ldsw + _i * 8192), 16, 0, 0); } while (0)
; #define PG8_LDA(dst, b, h) do { _Pragma("unroll") for (int m = 0; m < 4; ++m) _Pragma("unroll") for (int k = 0; k < 2; ++k) dst[m][k] = *(const LAS h16x8*)(lds + PG8_SA(b, h) + aoff + m * 2048 + k * 1024); } while (0)
; #define PG8_LDB(dst, b, h) do { _Pragma("unroll") for (int n = 0; n < 2; ++n) _Pragma("unroll") for (int k = 0; k < 2; ++k) dst[n][k] = *(const LAS h16x8*)(lds + PG8_SB(b, h) + boff + n * 2048 + k * 1024); } while (0)
; #define PG8_MMA(ai, bj, At, Bt_) do { __builtin_amdgcn_s_setprio(1); _Pragma("unroll") for (int m = 0; m < 4; ++m) _Pragma("unroll") for (int n = 0; n < 2; ++n) _Pragma("unroll") for (int k = 0; k < 2; ++k) \
;         acc[ai][bj][m][n] = __builtin_amdgcn_mfma_f32_16x16x32_f16(Bt_[n][k], At[m][k], acc[ai][bj][m][n], 0, 0, 0); __builtin_amdgcn_s_setprio(0); } while (0)
; #define PG8_WAIT_V(n) asm volatile("s_waitcnt vmcnt(" #n ")" ::: "memory")
; #define PG8_WAIT_L(n) asm volatile("s_waitcnt lgkmcnt(" #n ")" ::: "memory")
; #define PG8_BAR __builtin_amdgcn_s_barrier()
; #define PG8_SCHED __builtin_amdgcn_sched_barrier(0)
; template <class Epi, class AMap>
; __device__ __forceinline__ void gemm_phase(LAS unsigned char* lds, const AMap am, const int lda, const h16* Bt, const int ldb, const int M, const int N, const int K, const Epi& E) {
;     ...
;             PG8_LDB(B1, 1, 1); PG8_STAGE(PG8_SB(1, 0), b3, voffB);
;             PG8_BAR; PG8_WAIT_L(0); PG8_MMA(0, 1, At, B1); PG8_BAR;
;             PG8_LDA(At, 1, 1); PG8_STAGE(PG8_SA(1, 0), a3, voffA);
;             PG8_BAR; PG8_WAIT_L(0); PG8_MMA(1, 0, At, B0); PG8_BAR; PG8_SCHED;
;             PG8_STAGE(PG8_SB(1, 1), b3 + hstepB, voffB);
;             PG8_WAIT_V(6); PG8_BAR; PG8_MMA(1, 1, At, B1); PG8_BAR;
	global_load_lds_dwordx4 v[152:153], off
	v_lshl_add_u64 v[152:153], v[206:207], 0, s[92:93]
	s_add_i32 m0, s22, 0x2000
	s_nop 0
	global_load_lds_dwordx4 v[152:153], off
	s_mov_b32 m0, s80
	v_lshl_add_u64 v[152:153], v[212:213], 0, s[92:93]
	ds_read_b128 v[162:165], v157 offset:49152
	ds_read_b128 v[166:169], v157 offset:50176
	ds_read_b128 v[170:173], v157 offset:51200
	ds_read_b128 v[174:177], v157 offset:52224
	ds_read_b128 v[178:181], v157 offset:53248
	ds_read_b128 v[182:185], v157 offset:54272
	ds_read_b128 v[186:189], v157 offset:55296
	ds_read_b128 v[190:193], v157 offset:56320
	global_load_lds_dwordx4 v[152:153], off
	v_lshl_add_u64 v[152:153], v[224:225], 0, s[92:93]
	s_mov_b32 m0, s81
	s_nop 0
	global_load_lds_dwordx4 v[152:153], off
	s_add_u32 s22, s26, 0x10080
	s_addc_u32 s23, s27, 0
	s_add_i32 s26, s48, s73
	v_lshl_add_u64 v[232:233], s[22:23], 0, v[0:1]
	s_mov_b32 m0, s26
	s_nop 0
	global_load_lds_dwordx4 v[232:233], off
	v_lshl_add_u64 v[232:233], s[22:23], 0, v[142:143]
	s_add_i32 m0, s26, 0x2000
	s_nop 0
	global_load_lds_dwordx4 v[232:233], off
	s_add_u32 s29, s29, 0x100
	s_addc_u32 s45, s45, 0
	s_cmp_ge_i32 s51, s24
	s_mov_b64 s[22:23], s[0:1]
	s_mov_b32 s26, s51
	s_waitcnt vmcnt(8) lgkmcnt(0)
	s_barrier
	v_mfma_f32_16x16x32_f16 v[102:105], v[90:93], v[162:165], v[102:105]
	v_mfma_f32_16x16x32_f16 v[98:101], v[148:151], v[162:165], v[98:101]
	v_mfma_f32_16x16x32_f16 v[86:89], v[90:93], v[170:173], v[86:89]
	v_mfma_f32_16x16x32_f16 v[82:85], v[148:151], v[170:173], v[82:85]
	v_mfma_f32_16x16x32_f16 v[78:81], v[90:93], v[178:181], v[78:81]
	v_mfma_f32_16x16x32_f16 v[74:77], v[148:151], v[178:181], v[74:77]
	v_mfma_f32_16x16x32_f16 v[70:73], v[90:93], v[186:189], v[70:73]
	v_mfma_f32_16x16x32_f16 v[66:69], v[148:151], v[186:189], v[66:69]
	v_mfma_f32_16x16x32_f16 v[102:105], v[94:97], v[166:169], v[102:105]
	v_mfma_f32_16x16x32_f16 v[98:101], v[158:161], v[166:169], v[98:101]
	v_mfma_f32_16x16x32_f16 v[86:89], v[94:97], v[174:177], v[86:89]
	v_mfma_f32_16x16x32_f16 v[82:85], v[158:161], v[174:177], v[82:85]
	v_mfma_f32_16x16x32_f16 v[78:81], v[94:97], v[182:185], v[78:81]
	v_mfma_f32_16x16x32_f16 v[74:77], v[158:161], v[182:185], v[74:77]
	v_mfma_f32_16x16x32_f16 v[70:73], v[94:97], v[190:193], v[70:73]
	v_mfma_f32_16x16x32_f16 v[66:69], v[158:161], v[190:193], v[66:69]
	v_mfma_f32_16x16x32_f16 v[30:33], v[194:197], v[162:165], v[30:33]
	v_mfma_f32_16x16x32_f16 v[26:29], v[202:205], v[162:165], v[26:29]
	v_mfma_f32_16x16x32_f16 v[22:25], v[194:197], v[170:173], v[22:25]
	v_mfma_f32_16x16x32_f16 v[18:21], v[202:205], v[170:173], v[18:21]
	v_mfma_f32_16x16x32_f16 v[14:17], v[194:197], v[178:181], v[14:17]
	v_mfma_f32_16x16x32_f16 v[10:13], v[202:205], v[178:181], v[10:13]
	v_mfma_f32_16x16x32_f16 v[6:9], v[194:197], v[186:189], v[6:9]
	v_mfma_f32_16x16x32_f16 v[2:5], v[202:205], v[186:189], v[2:5]
	v_mfma_f32_16x16x32_f16 v[30:33], v[198:201], v[166:169], v[30:33]
	v_mfma_f32_16x16x32_f16 v[26:29], v[220:223], v[166:169], v[26:29]
	v_mfma_f32_16x16x32_f16 v[22:25], v[198:201], v[174:177], v[22:25]
	v_mfma_f32_16x16x32_f16 v[18:21], v[220:223], v[174:177], v[18:21]
	v_mfma_f32_16x16x32_f16 v[14:17], v[198:201], v[182:185], v[14:17]
	v_mfma_f32_16x16x32_f16 v[10:13], v[220:223], v[182:185], v[10:13]
	v_mfma_f32_16x16x32_f16 v[6:9], v[198:201], v[190:193], v[6:9]
	v_mfma_f32_16x16x32_f16 v[2:5], v[220:223], v[190:193], v[2:5]
	s_barrier
	s_cbranch_scc1 .Lg4x_621

; #define PG8_STAGE(bufoff, gbase, voff) do { _Pragma("unroll") for (int _i = 0; _i < 2; ++_i) \
;         __builtin_amdgcn_global_load_lds((const unsigned*)((const char*)(gbase) + (voff)[_i]), (LAS unsigned*)(lds + (bufoff) + ldsw + _i * 8192), 16, 0, 0); } while (0)
; #define PG8_LDA(dst, b, h) do { _Pragma("unroll") for (int m = 0; m < 4; ++m) _Pragma("unroll") for (int k = 0; k < 2; ++k) dst[m][k] = *(const LAS h16x8*)(lds + PG8_SA(b, h) + aoff + m * 2048 + k * 1024); } while (0)
; #define PG8_LDB(dst, b, h) do { _Pragma("unroll") for (int n = 0; n < 2; ++n) _Pragma("unroll") for (int k = 0; k < 2; ++k) dst[n][k] = *(const LAS h16x8*)(lds + PG8_SB(b, h) + boff + n * 2048 + k * 1024); } while (0)
; #define PG8_MMA(ai, bj, At, Bt_) do { __builtin_amdgcn_s_setprio(1); _Pragma("unroll") for (int m = 0; m < 4; ++m) _Pragma("unroll") for (int n = 0; n < 2; ++n) _Pragma("unroll") for (int k = 0; k < 2; ++k) \
;         acc[ai][bj][m][n] = __builtin_amdgcn_mfma_f32_16x16x32_f16(Bt_[n][k], At[m][k], acc[ai][bj][m][n], 0, 0, 0); __builtin_amdgcn_s_setprio(0); } while (0)
; template <class Epi, class AMap>
; __device__ __forceinline__ void gemm_phase(LAS unsigned char* lds, const AMap am, const int lda, const h16* Bt, const int ldb, const int M, const int N, const int K, const Epi& E) {
;     ...
;         const bool has_next = S.next(ui + 1, nxt);
;         const char* nA = has_next ? am(nxt.pn) + (size_t)nxt.pm * tstepA : cA; const char* nB = has_next ? (const char*)Bt + (size_t)nxt.pn * tstepB : cB;
; #pragma unroll 1
;         for (int t = 0; t < nt; t += 2) {
;             const bool last = (t == nt - 2);
;             const char* a1 = cA + (size_t)(t + 1) * kstep;
;             const char* a2 = last ? nA : cA + (size_t)(t + 2) * kstep; const char* b2 = last ? nB : cB + (size_t)(t + 2) * kstep;
;             const char* a3 = a2 + kstep; const char* b3 = b2 + kstep;
;             PG8_LDB(B0, 0, 0); PG8_SCHED; PG8_LDA(At, 0, 0); PG8_STAGE(PG8_SA(1, 1), a1 + hstepA, voffA);
;             PG8_WAIT_L(8); PG8_BAR; PG8_WAIT_L(0); PG8_MMA(0, 0, At, B0); PG8_BAR; PG8_SCHED;
;             PG8_LDB(B1, 0, 1); PG8_STAGE(PG8_SB(0, 0), b2, voffB);
;             PG8_BAR; PG8_WAIT_L(0); PG8_MMA(0, 1, At, B1); PG8_BAR;
;             PG8_LDA(At, 0, 1); PG8_STAGE(PG8_SA(0, 0), a2, voffA);
;             PG8_BAR; PG8_WAIT_L(0); PG8_MMA(1, 0, At, B0); PG8_BAR; PG8_SCHED;
.Lg4p_644:
	s_add_i32 s51, s26, 2
	s_add_u32 s0, s22, 0x100
	s_addc_u32 s1, s23, 0
	s_add_i32 s60, 0, 0x10000
	v_add_u32_e32 v234, s60, v203
	ds_read_b128 v[130:133], v234
	ds_read_b128 v[134:137], v234 offset:1024
	ds_read_b128 v[138:141], v234 offset:2048
	ds_read_b128 v[152:155], v234 offset:3072
	s_cmp_eq_u32 s80, s26
	s_cselect_b32 s26, s21, s29
	s_cselect_b32 s49, s47, s1
	s_cselect_b32 s48, s46, s0
	s_cselect_b32 s27, s20, s45
	v_lshl_add_u64 v[232:233], s[22:23], 0, v[148:149]
	s_add_i32 m0, s74, 0xc000
	ds_read_b128 v[156:159], v205
	ds_read_b128 v[160:163], v205 offset:1024
	ds_read_b128 v[164:167], v205 offset:2048
	ds_read_b128 v[168:171], v205 offset:3072
	ds_read_b128 v[172:175], v205 offset:4096
	ds_read_b128 v[176:179], v205 offset:5120
	ds_read_b128 v[180:183], v205 offset:6144
	ds_read_b128 v[184:187], v205 offset:7168
	global_load_lds_dwordx4 v[232:233], off
	v_lshl_add_u64 v[232:233], s[22:23], 0, v[150:151]
	s_add_i32 m0, s74, 0xe000
	s_nop 0
	global_load_lds_dwordx4 v[232:233], off
	s_waitcnt lgkmcnt(11)
	s_add_i32 s62, 0, 0x14000
	v_add_u32_e32 v200, s62, v203
	s_add_i32 s22, s60, s71
	ds_read_b128 v[188:191], v200
	ds_read_b128 v[192:195], v200 offset:1024
	ds_read_b128 v[196:199], v200 offset:2048
	ds_read_b128 v[220:223], v200 offset:3072
	s_waitcnt vmcnt(63) lgkmcnt(0)
	s_barrier
	v_mfma_f32_16x16x32_f16 v[122:125], v[130:133], v[156:159], 0
	v_mfma_f32_16x16x32_f16 v[126:129], v[138:141], v[156:159], 0
	v_mfma_f32_16x16x32_f16 v[110:113], v[130:133], v[164:167], 0
	v_mfma_f32_16x16x32_f16 v[106:109], v[138:141], v[164:167], 0
	v_mfma_f32_16x16x32_f16 v[94:97], v[130:133], v[172:175], 0
	v_mfma_f32_16x16x32_f16 v[90:93], v[138:141], v[172:175], 0
	v_mfma_f32_16x16x32_f16 v[78:81], v[130:133], v[180:183], 0
	v_mfma_f32_16x16x32_f16 v[74:77], v[138:141], v[180:183], 0
	v_mfma_f32_16x16x32_f16 v[122:125], v[134:137], v[160:163], v[122:125]
	v_mfma_f32_16x16x32_f16 v[126:129], v[152:155], v[160:163], v[126:129]
	v_mfma_f32_16x16x32_f16 v[110:113], v[134:137], v[168:171], v[110:113]
	v_mfma_f32_16x16x32_f16 v[106:109], v[152:155], v[168:171], v[106:109]
	v_mfma_f32_16x16x32_f16 v[94:97], v[134:137], v[176:179], v[94:97]
	v_mfma_f32_16x16x32_f16 v[90:93], v[152:155], v[176:179], v[90:93]
	v_mfma_f32_16x16x32_f16 v[78:81], v[134:137], v[184:187], v[78:81]
	v_mfma_f32_16x16x32_f16 v[74:77], v[152:155], v[184:187], v[74:77]
	v_mfma_f32_16x16x32_f16 v[118:121], v[188:191], v[156:159], 0
	v_mfma_f32_16x16x32_f16 v[114:117], v[196:199], v[156:159], 0
	v_mfma_f32_16x16x32_f16 v[102:105], v[188:191], v[164:167], 0
	v_mfma_f32_16x16x32_f16 v[98:101], v[196:199], v[164:167], 0
	v_mfma_f32_16x16x32_f16 v[86:89], v[188:191], v[172:175], 0
	v_mfma_f32_16x16x32_f16 v[82:85], v[196:199], v[172:175], 0
	v_mfma_f32_16x16x32_f16 v[70:73], v[188:191], v[180:183], 0
	v_mfma_f32_16x16x32_f16 v[66:69], v[196:199], v[180:183], 0
	v_mfma_f32_16x16x32_f16 v[118:121], v[192:195], v[160:163], v[118:121]
	v_mfma_f32_16x16x32_f16 v[114:117], v[220:223], v[160:163], v[114:117]
	v_mfma_f32_16x16x32_f16 v[102:105], v[192:195], v[168:171], v[102:105]
	v_mfma_f32_16x16x32_f16 v[98:101], v[220:223], v[168:171], v[98:101]
	v_mfma_f32_16x16x32_f16 v[86:89], v[192:195], v[176:179], v[86:89]
	v_mfma_f32_16x16x32_f16 v[82:85], v[220:223], v[176:179], v[82:85]
	v_mfma_f32_16x16x32_f16 v[70:73], v[192:195], v[184:187], v[70:73]
	v_mfma_f32_16x16x32_f16 v[66:69], v[220:223], v[184:187], v[66:69]
	s_barrier
	v_lshl_add_u64 v[200:201], s[26:27], 0, v[0:1]
	s_mov_b32 m0, s22
	v_lshl_add_u64 v[206:207], s[26:27], 0, v[146:147]
	global_load_lds_dwordx4 v[200:201], off
	s_add_i32 m0, s22, 0x2000
	s_nop 0
	global_load_lds_dwordx4 v[206:207], off
	s_mov_b32 m0, s74
	v_lshl_add_u64 v[212:213], s[48:49], 0, v[142:143]
	ds_read_b128 v[156:159], v205 offset:16384
	ds_read_b128 v[160:163], v205 offset:17408
	ds_read_b128 v[164:167], v205 offset:18432
	ds_read_b128 v[168:171], v205 offset:19456
	ds_read_b128 v[172:175], v205 offset:20480
	ds_read_b128 v[176:179], v205 offset:21504
	ds_read_b128 v[180:183], v205 offset:22528
	ds_read_b128 v[184:187], v205 offset:23552
	global_load_lds_dwordx4 v[212:213], off
	v_lshl_add_u64 v[224:225], s[48:49], 0, v[144:145]
	s_mov_b32 m0, s75
	s_nop 0
	global_load_lds_dwordx4 v[224:225], off
	s_add_u32 s22, s26, 0x10000
	s_addc_u32 s23, s27, 0
	s_add_i32 s60, s62, s71
	v_lshl_add_u64 v[232:233], s[22:23], 0, v[0:1]
	s_mov_b32 m0, s60
	s_nop 0
	global_load_lds_dwordx4 v[232:233], off
	v_lshl_add_u64 v[232:233], s[22:23], 0, v[146:147]
	s_add_i32 m0, s60, 0x2000
	s_nop 0
	global_load_lds_dwordx4 v[232:233], off
	s_waitcnt vmcnt(8) lgkmcnt(0)
	s_barrier
; #define PG8_STAGE(bufoff, gbase, voff) do { _Pragma("unroll") for (int _i = 0; _i < 2; ++_i) \
;         __builtin_amdgcn_global_load_lds((const unsigned*)((const char*)(gbase) + (voff)[_i]), (LAS unsigned*)(lds + (bufoff) + ldsw + _i * 8192), 16, 0, 0); } while (0)
; #define PG8_LDA(dst, b, h) do { _Pragma("unroll") for (int m = 0; m < 4; ++m) _Pragma("unroll") for (int k = 0; k < 2; ++k) dst[m][k] = *(const LAS h16x8*)(lds + PG8_SA(b, h) + aoff + m * 2048 + k * 1024); } while (0)
; #define PG8_LDB(dst, b, h) do { _Pragma("unroll") for (int n = 0; n < 2; ++n) _Pragma("unroll") for (int k = 0; k < 2; ++k) dst[n][k] = *(const LAS h16x8*)(lds + PG8_SB(b, h) + boff + n * 2048 + k * 1024); } while (0)
; #define PG8_MMA(ai, bj, At, Bt_) do { __builtin_amdgcn_s_setprio(1); _Pragma("unroll") for (int m = 0; m < 4; ++m) _Pragma("unroll") for (int n = 0; n < 2; ++n) _Pragma("unroll") for (int k = 0; k < 2; ++k) \
;         acc[ai][bj][m][n] = __builtin_amdgcn_mfma_f32_16x16x32_f16(Bt_[n][k], At[m][k], acc[ai][bj][m][n], 0, 0, 0); __builtin_amdgcn_s_setprio(0); } while (0)
; #define PG8_WAIT_V(n) asm volatile("s_waitcnt vmcnt(" #n ")" ::: "memory")
; #define PG8_WAIT_L(n) asm volatile("s_waitcnt lgkmcnt(" #n ")" ::: "memory")
; #define PG8_BAR __builtin_amdgcn_s_barrier()
; #define PG8_SCHED __builtin_amdgcn_sched_barrier(0)
; template <class Epi, class AMap>
; __device__ __forceinline__ void gemm_phase(LAS unsigned char* lds, const AMap am, const int lda, const h16* Bt, const int ldb, const int M, const int N, const int K, const Epi& E) {
;     ...
;             PG8_BAR; PG8_WAIT_L(0); PG8_MMA(1, 0, At, B0); PG8_BAR; PG8_SCHED;
;             PG8_STAGE(PG8_SB(0, 1), b2 + hstepB, voffB);
;             PG8_WAIT_V(6); PG8_BAR; PG8_MMA(1, 1, At, B1); PG8_BAR;
;             PG8_LDB(B0, 1, 0); PG8_SCHED; PG8_LDA(At, 1, 0); PG8_STAGE(PG8_SA(0, 1), a2 + hstepA, voffA);
;             PG8_WAIT_L(8); PG8_BAR; PG8_WAIT_L(0); PG8_MMA(0, 0, At, B0); PG8_BAR; PG8_SCHED;
;             PG8_LDB(B1, 1, 1); PG8_STAGE(PG8_SB(1, 0), b3, voffB);
;             PG8_BAR; PG8_WAIT_L(0); PG8_MMA(0, 1, At, B1); PG8_BAR;
	v_mfma_f32_16x16x32_f16 v[62:65], v[130:133], v[156:159], 0
	v_mfma_f32_16x16x32_f16 v[58:61], v[138:141], v[156:159], 0
	v_mfma_f32_16x16x32_f16 v[46:49], v[130:133], v[164:167], 0
	v_mfma_f32_16x16x32_f16 v[42:45], v[138:141], v[164:167], 0
	v_mfma_f32_16x16x32_f16 v[30:33], v[130:133], v[172:175], 0
	v_mfma_f32_16x16x32_f16 v[26:29], v[138:141], v[172:175], 0
	v_mfma_f32_16x16x32_f16 v[14:17], v[130:133], v[180:183], 0
	v_mfma_f32_16x16x32_f16 v[10:13], v[138:141], v[180:183], 0
	v_mfma_f32_16x16x32_f16 v[62:65], v[134:137], v[160:163], v[62:65]
	v_mfma_f32_16x16x32_f16 v[58:61], v[152:155], v[160:163], v[58:61]
	v_mfma_f32_16x16x32_f16 v[46:49], v[134:137], v[168:171], v[46:49]
	v_mfma_f32_16x16x32_f16 v[42:45], v[152:155], v[168:171], v[42:45]
	v_mfma_f32_16x16x32_f16 v[30:33], v[134:137], v[176:179], v[30:33]
	v_mfma_f32_16x16x32_f16 v[26:29], v[152:155], v[176:179], v[26:29]
	v_mfma_f32_16x16x32_f16 v[14:17], v[134:137], v[184:187], v[14:17]
	v_mfma_f32_16x16x32_f16 v[10:13], v[152:155], v[184:187], v[10:13]
	v_mfma_f32_16x16x32_f16 v[54:57], v[188:191], v[156:159], 0
	v_mfma_f32_16x16x32_f16 v[50:53], v[196:199], v[156:159], 0
	v_mfma_f32_16x16x32_f16 v[38:41], v[188:191], v[164:167], 0
	v_mfma_f32_16x16x32_f16 v[34:37], v[196:199], v[164:167], 0
	v_mfma_f32_16x16x32_f16 v[22:25], v[188:191], v[172:175], 0
	v_mfma_f32_16x16x32_f16 v[18:21], v[196:199], v[172:175], 0
	v_mfma_f32_16x16x32_f16 v[6:9], v[188:191], v[180:183], 0
	v_mfma_f32_16x16x32_f16 v[2:5], v[196:199], v[180:183], 0
	v_mfma_f32_16x16x32_f16 v[54:57], v[192:195], v[160:163], v[54:57]
	v_mfma_f32_16x16x32_f16 v[50:53], v[220:223], v[160:163], v[50:53]
	v_mfma_f32_16x16x32_f16 v[38:41], v[192:195], v[168:171], v[38:41]
	v_mfma_f32_16x16x32_f16 v[34:37], v[220:223], v[168:171], v[34:37]
	v_mfma_f32_16x16x32_f16 v[22:25], v[192:195], v[176:179], v[22:25]
	v_mfma_f32_16x16x32_f16 v[18:21], v[220:223], v[176:179], v[18:21]
	v_mfma_f32_16x16x32_f16 v[6:9], v[192:195], v[184:187], v[6:9]
	v_mfma_f32_16x16x32_f16 v[2:5], v[220:223], v[184:187], v[2:5]
	s_barrier
	s_add_i32 s60, 0, 0x18000
	v_add_u32_e32 v234, s60, v203
	ds_read_b128 v[130:133], v234
	ds_read_b128 v[134:137], v234 offset:1024
	ds_read_b128 v[138:141], v234 offset:2048
	ds_read_b128 v[152:155], v234 offset:3072
	s_add_u32 s22, s48, 0x1c0000
	s_addc_u32 s23, s49, 0
	s_mov_b32 m0, s76
	v_lshl_add_u64 v[232:233], s[22:23], 0, v[142:143]
	ds_read_b128 v[156:159], v205 offset:32768
	ds_read_b128 v[160:163], v205 offset:33792
	ds_read_b128 v[164:167], v205 offset:34816
	ds_read_b128 v[168:171], v205 offset:35840
	ds_read_b128 v[172:175], v205 offset:36864
	ds_read_b128 v[176:179], v205 offset:37888
	ds_read_b128 v[180:183], v205 offset:38912
	ds_read_b128 v[184:187], v205 offset:39936
	global_load_lds_dwordx4 v[232:233], off
	v_lshl_add_u64 v[232:233], s[22:23], 0, v[144:145]
	s_mov_b32 m0, s77
	s_nop 0
	global_load_lds_dwordx4 v[232:233], off
	s_waitcnt lgkmcnt(11)
	s_add_i32 s48, 0, 0x1c000
	s_add_i32 s22, s60, s71
	v_add_u32_e32 v214, s48, v203
	v_lshl_add_u64 v[200:201], v[200:201], 0, s[92:93]
	s_mov_b32 m0, s22
	ds_read_b128 v[188:191], v214
	ds_read_b128 v[192:195], v214 offset:1024
	ds_read_b128 v[196:199], v214 offset:2048
	ds_read_b128 v[220:223], v214 offset:3072
	s_waitcnt vmcnt(8) lgkmcnt(0)
	s_barrier
	v_mfma_f32_16x16x32_f16 v[122:125], v[130:133], v[156:159], v[122:125]
	v_mfma_f32_16x16x32_f16 v[126:129], v[138:141], v[156:159], v[126:129]
	v_mfma_f32_16x16x32_f16 v[110:113], v[130:133], v[164:167], v[110:113]
	v_mfma_f32_16x16x32_f16 v[106:109], v[138:141], v[164:167], v[106:109]
	v_mfma_f32_16x16x32_f16 v[94:97], v[130:133], v[172:175], v[94:97]
	v_mfma_f32_16x16x32_f16 v[90:93], v[138:141], v[172:175], v[90:93]
	v_mfma_f32_16x16x32_f16 v[78:81], v[130:133], v[180:183], v[78:81]
	v_mfma_f32_16x16x32_f16 v[74:77], v[138:141], v[180:183], v[74:77]
	v_mfma_f32_16x16x32_f16 v[122:125], v[134:137], v[160:163], v[122:125]
	v_mfma_f32_16x16x32_f16 v[126:129], v[152:155], v[160:163], v[126:129]
	v_mfma_f32_16x16x32_f16 v[110:113], v[134:137], v[168:171], v[110:113]
	v_mfma_f32_16x16x32_f16 v[106:109], v[152:155], v[168:171], v[106:109]
	v_mfma_f32_16x16x32_f16 v[94:97], v[134:137], v[176:179], v[94:97]
	v_mfma_f32_16x16x32_f16 v[90:93], v[152:155], v[176:179], v[90:93]
	v_mfma_f32_16x16x32_f16 v[78:81], v[134:137], v[184:187], v[78:81]
	v_mfma_f32_16x16x32_f16 v[74:77], v[152:155], v[184:187], v[74:77]
	v_mfma_f32_16x16x32_f16 v[118:121], v[188:191], v[156:159], v[118:121]
	v_mfma_f32_16x16x32_f16 v[114:117], v[196:199], v[156:159], v[114:117]
	v_mfma_f32_16x16x32_f16 v[102:105], v[188:191], v[164:167], v[102:105]
	v_mfma_f32_16x16x32_f16 v[98:101], v[196:199], v[164:167], v[98:101]
	v_mfma_f32_16x16x32_f16 v[86:89], v[188:191], v[172:175], v[86:89]
	v_mfma_f32_16x16x32_f16 v[82:85], v[196:199], v[172:175], v[82:85]
	v_mfma_f32_16x16x32_f16 v[70:73], v[188:191], v[180:183], v[70:73]
	v_mfma_f32_16x16x32_f16 v[66:69], v[196:199], v[180:183], v[66:69]
	v_mfma_f32_16x16x32_f16 v[118:121], v[192:195], v[160:163], v[118:121]
	v_mfma_f32_16x16x32_f16 v[114:117], v[220:223], v[160:163], v[114:117]
	v_mfma_f32_16x16x32_f16 v[102:105], v[192:195], v[168:171], v[102:105]
	v_mfma_f32_16x16x32_f16 v[98:101], v[220:223], v[168:171], v[98:101]
	v_mfma_f32_16x16x32_f16 v[86:89], v[192:195], v[176:179], v[86:89]
	v_mfma_f32_16x16x32_f16 v[82:85], v[220:223], v[176:179], v[82:85]
	v_mfma_f32_16x16x32_f16 v[70:73], v[192:195], v[184:187], v[70:73]
	v_mfma_f32_16x16x32_f16 v[66:69], v[220:223], v[184:187], v[66:69]
	s_barrier
; #define PG8_STAGE(bufoff, gbase, voff) do { _Pragma("unroll") for (int _i = 0; _i < 2; ++_i) \
;         __builtin_amdgcn_global_load_lds((const unsigned*)((const char*)(gbase) + (voff)[_i]), (LAS unsigned*)(lds + (bufoff) + ldsw + _i * 8192), 16, 0, 0); } while (0)
; #define PG8_LDA(dst, b, h) do { _Pragma("unroll") for (int m = 0; m < 4; ++m) _Pragma("unroll") for (int k = 0; k < 2; ++k) dst[m][k] = *(const LAS h16x8*)(lds + PG8_SA(b, h) + aoff + m * 2048 + k * 1024); } while (0)
; #define PG8_LDB(dst, b, h) do { _Pragma("unroll") for (int n = 0; n < 2; ++n) _Pragma("unroll") for (int k = 0; k < 2; ++k) dst[n][k] = *(const LAS h16x8*)(lds + PG8_SB(b, h) + boff + n * 2048 + k * 1024); } while (0)
; #define PG8_MMA(ai, bj, At, Bt_) do { __builtin_amdgcn_s_setprio(1); _Pragma("unroll") for (int m = 0; m < 4; ++m) _Pragma("unroll") for (int n = 0; n < 2; ++n) _Pragma("unroll") for (int k = 0; k < 2; ++k) \
;         acc[ai][bj][m][n] = __builtin_amdgcn_mfma_f32_16x16x32_f16(Bt_[n][k], At[m][k], acc[ai][bj][m][n], 0, 0, 0); __builtin_amdgcn_s_setprio(0); } while (0)
; #define PG8_WAIT_V(n) asm volatile("s_waitcnt vmcnt(" #n ")" ::: "memory")
; #define PG8_WAIT_L(n) asm volatile("s_waitcnt lgkmcnt(" #n ")" ::: "memory")
; #define PG8_BAR __builtin_amdgcn_s_barrier()
; #define PG8_SCHED __builtin_amdgcn_sched_barrier(0)
; template <class Epi, class AMap>
; __device__ __forceinline__ void gemm_phase(LAS unsigned char* lds, const AMap am, const int lda, const h16* Bt, const int ldb, const int M, const int N, const int K, const Epi& E) {
;     ...
;             PG8_LDB(B1, 1, 1); PG8_STAGE(PG8_SB(1, 0), b3, voffB);
;             PG8_BAR; PG8_WAIT_L(0); PG8_MMA(0, 1, At, B1); PG8_BAR;
;             PG8_LDA(At, 1, 1); PG8_STAGE(PG8_SA(1, 0), a3, voffA);
;             PG8_BAR; PG8_WAIT_L(0); PG8_MMA(1, 0, At, B0); PG8_BAR; PG8_SCHED;
;             PG8_STAGE(PG8_SB(1, 1), b3 + hstepB, voffB);
;             PG8_WAIT_V(6); PG8_BAR; PG8_MMA(1, 1, At, B1); PG8_BAR;
	global_load_lds_dwordx4 v[200:201], off
	v_lshl_add_u64 v[200:201], v[206:207], 0, s[92:93]
	s_add_i32 m0, s22, 0x2000
	s_nop 0
	global_load_lds_dwordx4 v[200:201], off
	s_mov_b32 m0, s78
	v_lshl_add_u64 v[200:201], v[212:213], 0, s[92:93]
	ds_read_b128 v[156:159], v205 offset:49152
	ds_read_b128 v[160:163], v205 offset:50176
	ds_read_b128 v[164:167], v205 offset:51200
	ds_read_b128 v[168:171], v205 offset:52224
	ds_read_b128 v[172:175], v205 offset:53248
	ds_read_b128 v[176:179], v205 offset:54272
	ds_read_b128 v[180:183], v205 offset:55296
	ds_read_b128 v[184:187], v205 offset:56320
	global_load_lds_dwordx4 v[200:201], off
	v_lshl_add_u64 v[200:201], v[224:225], 0, s[92:93]
	s_mov_b32 m0, s79
	s_nop 0
	global_load_lds_dwordx4 v[200:201], off
	s_add_u32 s22, s26, 0x10080
	s_addc_u32 s23, s27, 0
	s_add_i32 s26, s48, s71
	v_lshl_add_u64 v[232:233], s[22:23], 0, v[0:1]
	s_mov_b32 m0, s26
	s_nop 0
	global_load_lds_dwordx4 v[232:233], off
	v_lshl_add_u64 v[232:233], s[22:23], 0, v[146:147]
	s_add_i32 m0, s26, 0x2000
	s_nop 0
	global_load_lds_dwordx4 v[232:233], off
	s_add_u32 s29, s29, 0x100
	s_addc_u32 s45, s45, 0
	s_cmp_ge_i32 s51, s24
	s_mov_b64 s[22:23], s[0:1]
	s_mov_b32 s26, s51
	s_waitcnt vmcnt(8) lgkmcnt(0)
	s_barrier
	v_mfma_f32_16x16x32_f16 v[62:65], v[130:133], v[156:159], v[62:65]
	v_mfma_f32_16x16x32_f16 v[58:61], v[138:141], v[156:159], v[58:61]
	v_mfma_f32_16x16x32_f16 v[46:49], v[130:133], v[164:167], v[46:49]
	v_mfma_f32_16x16x32_f16 v[42:45], v[138:141], v[164:167], v[42:45]
	v_mfma_f32_16x16x32_f16 v[30:33], v[130:133], v[172:175], v[30:33]
	v_mfma_f32_16x16x32_f16 v[26:29], v[138:141], v[172:175], v[26:29]
	v_mfma_f32_16x16x32_f16 v[14:17], v[130:133], v[180:183], v[14:17]
	v_mfma_f32_16x16x32_f16 v[10:13], v[138:141], v[180:183], v[10:13]
	v_mfma_f32_16x16x32_f16 v[62:65], v[134:137], v[160:163], v[62:65]
	v_mfma_f32_16x16x32_f16 v[58:61], v[152:155], v[160:163], v[58:61]
	v_mfma_f32_16x16x32_f16 v[46:49], v[134:137], v[168:171], v[46:49]
	v_mfma_f32_16x16x32_f16 v[42:45], v[152:155], v[168:171], v[42:45]
	v_mfma_f32_16x16x32_f16 v[30:33], v[134:137], v[176:179], v[30:33]
	v_mfma_f32_16x16x32_f16 v[26:29], v[152:155], v[176:179], v[26:29]
	v_mfma_f32_16x16x32_f16 v[14:17], v[134:137], v[184:187], v[14:17]
	v_mfma_f32_16x16x32_f16 v[10:13], v[152:155], v[184:187], v[10:13]
	v_mfma_f32_16x16x32_f16 v[54:57], v[188:191], v[156:159], v[54:57]
	v_mfma_f32_16x16x32_f16 v[50:53], v[196:199], v[156:159], v[50:53]
	v_mfma_f32_16x16x32_f16 v[38:41], v[188:191], v[164:167], v[38:41]
	v_mfma_f32_16x16x32_f16 v[34:37], v[196:199], v[164:167], v[34:37]
	v_mfma_f32_16x16x32_f16 v[22:25], v[188:191], v[172:175], v[22:25]
	v_mfma_f32_16x16x32_f16 v[18:21], v[196:199], v[172:175], v[18:21]
	v_mfma_f32_16x16x32_f16 v[6:9], v[188:191], v[180:183], v[6:9]
	v_mfma_f32_16x16x32_f16 v[2:5], v[196:199], v[180:183], v[2:5]
	v_mfma_f32_16x16x32_f16 v[54:57], v[192:195], v[160:163], v[54:57]
	v_mfma_f32_16x16x32_f16 v[50:53], v[220:223], v[160:163], v[50:53]
	v_mfma_f32_16x16x32_f16 v[38:41], v[192:195], v[168:171], v[38:41]
	v_mfma_f32_16x16x32_f16 v[34:37], v[220:223], v[168:171], v[34:37]
	v_mfma_f32_16x16x32_f16 v[22:25], v[192:195], v[176:179], v[22:25]
	v_mfma_f32_16x16x32_f16 v[18:21], v[220:223], v[176:179], v[18:21]
	v_mfma_f32_16x16x32_f16 v[6:9], v[192:195], v[184:187], v[6:9]
	v_mfma_f32_16x16x32_f16 v[2:5], v[220:223], v[184:187], v[2:5]
	s_barrier
	s_cbranch_scc1 .Lg4x_644

; #define PG8_STAGE(bufoff, gbase, voff) do { _Pragma("unroll") for (int _i = 0; _i < 2; ++_i) \
;         __builtin_amdgcn_global_load_lds((const unsigned*)((const char*)(gbase) + (voff)[_i]), (LAS unsigned*)(lds + (bufoff) + ldsw + _i * 8192), 16, 0, 0); } while (0)
; #define PG8_LDA(dst, b, h) do { _Pragma("unroll") for (int m = 0; m < 4; ++m) _Pragma("unroll") for (int k = 0; k < 2; ++k) dst[m][k] = *(const LAS h16x8*)(lds + PG8_SA(b, h) + aoff + m * 2048 + k * 1024); } while (0)
; #define PG8_LDB(dst, b, h) do { _Pragma("unroll") for (int n = 0; n < 2; ++n) _Pragma("unroll") for (int k = 0; k < 2; ++k) dst[n][k] = *(const LAS h16x8*)(lds + PG8_SB(b, h) + boff + n * 2048 + k * 1024); } while (0)
; #define PG8_MMA(ai, bj, At, Bt_) do { __builtin_amdgcn_s_setprio(1); _Pragma("unroll") for (int m = 0; m < 4; ++m) _Pragma("unroll") for (int n = 0; n < 2; ++n) _Pragma("unroll") for (int k = 0; k < 2; ++k) \
;         acc[ai][bj][m][n] = __builtin_amdgcn_mfma_f32_16x16x32_f16(Bt_[n][k], At[m][k], acc[ai][bj][m][n], 0, 0, 0); __builtin_amdgcn_s_setprio(0); } while (0)
; template <class Epi, class AMap>
; __device__ __forceinline__ void gemm_phase(LAS unsigned char* lds, const AMap am, const int lda, const h16* Bt, const int ldb, const int M, const int N, const int K, const Epi& E) {
;     ...
;     f32x4 acc[2][2][4][2];
; #pragma unroll
;     for (int a = 0; a < 2; ++a)
; #pragma unroll
;         for (int b = 0; b < 2; ++b)
; #pragma unroll
;             for (int m = 0; m < 4; ++m)
; #pragma unroll
;                 for (int n = 0; n < 2; ++n) acc[a][b][m][n] = (f32x4){0.f, 0.f, 0.f, 0.f};
;     ...
;         const bool has_next = S.next(ui + 1, nxt);
;         const char* nA = has_next ? am(nxt.pn) + (size_t)nxt.pm * tstepA : cA; const char* nB = has_next ? (const char*)Bt + (size_t)nxt.pn * tstepB : cB;
; #pragma unroll 1
;         for (int t = 0; t < nt; t += 2) {
;             const bool last = (t == nt - 2);
;             const char* a1 = cA + (size_t)(t + 1) * kstep;
;             const char* a2 = last ? nA : cA + (size_t)(t + 2) * kstep; const char* b2 = last ? nB : cB + (size_t)(t + 2) * kstep;
;             const char* a3 = a2 + kstep; const char* b3 = b2 + kstep;
;             PG8_LDB(B0, 0, 0); PG8_SCHED; PG8_LDA(At, 0, 0); PG8_STAGE(PG8_SA(1, 1), a1 + hstepA, voffA);
;             PG8_WAIT_L(8); PG8_BAR; PG8_WAIT_L(0); PG8_MMA(0, 0, At, B0); PG8_BAR; PG8_SCHED;
.LBB0_665:
	s_ashr_i32 s27, s26, 31
	s_lshl_b64 s[20:21], s[26:27], 17
	s_add_u32 s42, s63, s20
	s_addc_u32 s43, s64, s21
	v_mov_b32_e32 v129, 0
	s_andn2_b64 vcc, exec, s[22:23]
	v_mov_b32_e32 v128, 0
	v_mov_b32_e32 v127, 0
	v_mov_b32_e32 v126, 0
	v_mov_b32_e32 v125, 0
	v_mov_b32_e32 v124, 0
	v_mov_b32_e32 v123, 0
	v_mov_b32_e32 v122, 0
	v_mov_b32_e32 v121, 0
	v_mov_b32_e32 v120, 0
	v_mov_b32_e32 v119, 0
	v_mov_b32_e32 v118, 0
	v_mov_b32_e32 v117, 0
	v_mov_b32_e32 v116, 0
	v_mov_b32_e32 v115, 0
	v_mov_b32_e32 v114, 0
	v_mov_b32_e32 v113, 0
	v_mov_b32_e32 v112, 0
	v_mov_b32_e32 v111, 0
	v_mov_b32_e32 v110, 0
	v_mov_b32_e32 v109, 0
	v_mov_b32_e32 v108, 0
	v_mov_b32_e32 v107, 0
	v_mov_b32_e32 v106, 0
	v_mov_b32_e32 v105, 0
	v_mov_b32_e32 v104, 0
	v_mov_b32_e32 v103, 0
	v_mov_b32_e32 v102, 0
	v_mov_b32_e32 v101, 0
	v_mov_b32_e32 v100, 0
	v_mov_b32_e32 v99, 0
	v_mov_b32_e32 v98, 0
	v_mov_b32_e32 v35, 0
	v_mov_b32_e32 v34, 0
	v_mov_b32_e32 v37, 0
	v_mov_b32_e32 v36, 0
	v_mov_b32_e32 v51, 0
	v_mov_b32_e32 v50, 0
	v_mov_b32_e32 v53, 0
	v_mov_b32_e32 v52, 0
	v_mov_b32_e32 v43, 0
	v_mov_b32_e32 v42, 0
	v_mov_b32_e32 v45, 0
	v_mov_b32_e32 v44, 0
	v_mov_b32_e32 v67, 0
	v_mov_b32_e32 v66, 0
	v_mov_b32_e32 v69, 0
	v_mov_b32_e32 v68, 0
	v_mov_b32_e32 v59, 0
	v_mov_b32_e32 v58, 0
	v_mov_b32_e32 v61, 0
	v_mov_b32_e32 v60, 0
	v_mov_b32_e32 v57, 0
	v_mov_b32_e32 v56, 0
	v_mov_b32_e32 v55, 0
	v_mov_b32_e32 v54, 0
	v_mov_b32_e32 v49, 0
	v_mov_b32_e32 v48, 0
	v_mov_b32_e32 v47, 0
	v_mov_b32_e32 v46, 0
	v_mov_b32_e32 v41, 0
	v_mov_b32_e32 v40, 0
	v_mov_b32_e32 v39, 0
	v_mov_b32_e32 v38, 0
	v_mov_b32_e32 v93, 0
	v_mov_b32_e32 v92, 0
	v_mov_b32_e32 v91, 0
	v_mov_b32_e32 v90, 0
	v_mov_b32_e32 v145, 0
	v_mov_b32_e32 v144, 0
	v_mov_b32_e32 v153, 0
	v_mov_b32_e32 v152, 0
	v_mov_b32_e32 v77, 0
	v_mov_b32_e32 v76, 0
	v_mov_b32_e32 v85, 0
	v_mov_b32_e32 v84, 0
	v_mov_b32_e32 v147, 0
	v_mov_b32_e32 v146, 0
	v_mov_b32_e32 v155, 0
	v_mov_b32_e32 v154, 0
	v_mov_b32_e32 v75, 0
	v_mov_b32_e32 v74, 0
	v_mov_b32_e32 v141, 0
	v_mov_b32_e32 v140, 0
	v_mov_b32_e32 v149, 0
	v_mov_b32_e32 v148, 0
	v_mov_b32_e32 v157, 0
	v_mov_b32_e32 v156, 0
	v_mov_b32_e32 v83, 0
	v_mov_b32_e32 v82, 0
	v_mov_b32_e32 v143, 0
	v_mov_b32_e32 v142, 0
	v_mov_b32_e32 v151, 0
	v_mov_b32_e32 v150, 0
	v_mov_b32_e32 v159, 0
	v_mov_b32_e32 v158, 0
	v_mov_b32_e32 v33, 0
	v_mov_b32_e32 v32, 0
	v_mov_b32_e32 v31, 0
	v_mov_b32_e32 v30, 0
	v_mov_b32_e32 v29, 0
	v_mov_b32_e32 v28, 0
	v_mov_b32_e32 v27, 0
	v_mov_b32_e32 v26, 0
	v_mov_b32_e32 v25, 0
	v_mov_b32_e32 v24, 0
	v_mov_b32_e32 v23, 0
	v_mov_b32_e32 v22, 0
	v_mov_b32_e32 v21, 0
	v_mov_b32_e32 v20, 0
	v_mov_b32_e32 v19, 0
	v_mov_b32_e32 v18, 0
	v_mov_b32_e32 v17, 0
	v_mov_b32_e32 v16, 0
	v_mov_b32_e32 v15, 0
	v_mov_b32_e32 v14, 0
	v_mov_b32_e32 v13, 0
	v_mov_b32_e32 v12, 0
	v_mov_b32_e32 v11, 0
	v_mov_b32_e32 v10, 0
	v_mov_b32_e32 v9, 0
	v_mov_b32_e32 v8, 0
	v_mov_b32_e32 v7, 0
	v_mov_b32_e32 v6, 0
	v_mov_b32_e32 v5, 0
	v_mov_b32_e32 v4, 0
	v_mov_b32_e32 v3, 0
	v_mov_b32_e32 v2, 0
	s_cbranch_vccnz .LBB0_656
	s_and_b64 s[0:1], s[0:1], exec
	s_cselect_b32 s20, s43, s47
	s_cselect_b32 s21, s42, s46
	s_add_u32 s27, s46, 0x100
	s_addc_u32 s29, s47, 0
	s_mov_b32 s46, 0
.Lg4p_667:
	s_add_i32 s60, s46, 2
	s_add_u32 s0, s44, 0x100
	s_addc_u32 s1, s45, 0
	s_add_i32 s66, 0, 0x10000
	v_add_u32_e32 v234, s66, v161
	ds_read_b128 v[140:143], v234
	ds_read_b128 v[144:147], v234 offset:1024
	ds_read_b128 v[148:151], v234 offset:2048
	ds_read_b128 v[152:155], v234 offset:3072
	s_cmp_eq_u32 s73, s46
	s_cselect_b32 s46, s21, s27
	s_cselect_b32 s49, s41, s1
	s_cselect_b32 s48, s40, s0
	s_cselect_b32 s47, s20, s29
	v_lshl_add_u64 v[232:233], s[44:45], 0, v[136:137]
	s_add_i32 m0, s65, 0xc000
	ds_read_b128 v[156:159], v163
	ds_read_b128 v[164:167], v163 offset:1024
	ds_read_b128 v[168:171], v163 offset:2048
	ds_read_b128 v[172:175], v163 offset:3072
	ds_read_b128 v[176:179], v163 offset:4096
	ds_read_b128 v[180:183], v163 offset:5120
	ds_read_b128 v[184:187], v163 offset:6144
	ds_read_b128 v[188:191], v163 offset:7168
	global_load_lds_dwordx4 v[232:233], off
	v_lshl_add_u64 v[232:233], s[44:45], 0, v[138:139]
	s_add_i32 m0, s65, 0xe000
	s_nop 0
	global_load_lds_dwordx4 v[232:233], off
	s_waitcnt lgkmcnt(11)
	s_add_i32 s78, 0, 0x14000
	s_add_i32 s44, s66, s62
	v_add_u32_e32 v234, s78, v161
	v_lshl_add_u64 v[212:213], s[46:47], 0, v[0:1]
	s_mov_b32 m0, s44
	ds_read_b128 v[192:195], v234
	ds_read_b128 v[196:199], v234 offset:1024
	ds_read_b128 v[200:203], v234 offset:2048
	ds_read_b128 v[204:207], v234 offset:3072
	s_waitcnt vmcnt(24) lgkmcnt(0)
	s_barrier
; #define PG8_STAGE(bufoff, gbase, voff) do { _Pragma("unroll") for (int _i = 0; _i < 2; ++_i) \
;         __builtin_amdgcn_global_load_lds((const unsigned*)((const char*)(gbase) + (voff)[_i]), (LAS unsigned*)(lds + (bufoff) + ldsw + _i * 8192), 16, 0, 0); } while (0)
; #define PG8_LDA(dst, b, h) do { _Pragma("unroll") for (int m = 0; m < 4; ++m) _Pragma("unroll") for (int k = 0; k < 2; ++k) dst[m][k] = *(const LAS h16x8*)(lds + PG8_SA(b, h) + aoff + m * 2048 + k * 1024); } while (0)
; #define PG8_LDB(dst, b, h) do { _Pragma("unroll") for (int n = 0; n < 2; ++n) _Pragma("unroll") for (int k = 0; k < 2; ++k) dst[n][k] = *(const LAS h16x8*)(lds + PG8_SB(b, h) + boff + n * 2048 + k * 1024); } while (0)
; #define PG8_MMA(ai, bj, At, Bt_) do { __builtin_amdgcn_s_setprio(1); _Pragma("unroll") for (int m = 0; m < 4; ++m) _Pragma("unroll") for (int n = 0; n < 2; ++n) _Pragma("unroll") for (int k = 0; k < 2; ++k) \
;         acc[ai][bj][m][n] = __builtin_amdgcn_mfma_f32_16x16x32_f16(Bt_[n][k], At[m][k], acc[ai][bj][m][n], 0, 0, 0); __builtin_amdgcn_s_setprio(0); } while (0)
; #define PG8_WAIT_V(n) asm volatile("s_waitcnt vmcnt(" #n ")" ::: "memory")
; #define PG8_WAIT_L(n) asm volatile("s_waitcnt lgkmcnt(" #n ")" ::: "memory")
; #define PG8_BAR __builtin_amdgcn_s_barrier()
; #define PG8_SCHED __builtin_amdgcn_sched_barrier(0)
; template <class Epi, class AMap>
; __device__ __forceinline__ void gemm_phase(LAS unsigned char* lds, const AMap am, const int lda, const h16* Bt, const int ldb, const int M, const int N, const int K, const Epi& E) {
;     ...
;             PG8_WAIT_L(8); PG8_BAR; PG8_WAIT_L(0); PG8_MMA(0, 0, At, B0); PG8_BAR; PG8_SCHED;
;             PG8_LDB(B1, 0, 1); PG8_STAGE(PG8_SB(0, 0), b2, voffB);
;             PG8_BAR; PG8_WAIT_L(0); PG8_MMA(0, 1, At, B1); PG8_BAR;
;             PG8_LDA(At, 0, 1); PG8_STAGE(PG8_SA(0, 0), a2, voffA);
;             PG8_BAR; PG8_WAIT_L(0); PG8_MMA(1, 0, At, B0); PG8_BAR; PG8_SCHED;
;             PG8_STAGE(PG8_SB(0, 1), b2 + hstepB, voffB);
;             PG8_WAIT_V(6); PG8_BAR; PG8_MMA(1, 1, At, B1); PG8_BAR;
	v_mfma_f32_16x16x32_f16 v[126:129], v[140:143], v[156:159], 0
	v_mfma_f32_16x16x32_f16 v[122:125], v[148:151], v[156:159], 0
	v_mfma_f32_16x16x32_f16 v[118:121], v[140:143], v[168:171], 0
	v_mfma_f32_16x16x32_f16 v[114:117], v[148:151], v[168:171], 0
	v_mfma_f32_16x16x32_f16 v[110:113], v[140:143], v[176:179], 0
	v_mfma_f32_16x16x32_f16 v[106:109], v[148:151], v[176:179], 0
	v_mfma_f32_16x16x32_f16 v[102:105], v[140:143], v[184:187], 0
	v_mfma_f32_16x16x32_f16 v[98:101], v[148:151], v[184:187], 0
	v_mfma_f32_16x16x32_f16 v[126:129], v[144:147], v[164:167], v[126:129]
	v_mfma_f32_16x16x32_f16 v[122:125], v[152:155], v[164:167], v[122:125]
	v_mfma_f32_16x16x32_f16 v[118:121], v[144:147], v[172:175], v[118:121]
	v_mfma_f32_16x16x32_f16 v[114:117], v[152:155], v[172:175], v[114:117]
	v_mfma_f32_16x16x32_f16 v[110:113], v[144:147], v[180:183], v[110:113]
	v_mfma_f32_16x16x32_f16 v[106:109], v[152:155], v[180:183], v[106:109]
	v_mfma_f32_16x16x32_f16 v[102:105], v[144:147], v[188:191], v[102:105]
	v_mfma_f32_16x16x32_f16 v[98:101], v[152:155], v[188:191], v[98:101]
	v_mfma_f32_16x16x32_f16 v[94:97], v[192:195], v[156:159], 0
	v_mfma_f32_16x16x32_f16 v[86:89], v[200:203], v[156:159], 0
	v_mfma_f32_16x16x32_f16 v[78:81], v[192:195], v[168:171], 0
	v_mfma_f32_16x16x32_f16 v[70:73], v[200:203], v[168:171], 0
	v_mfma_f32_16x16x32_f16 v[62:65], v[192:195], v[176:179], 0
	v_mfma_f32_16x16x32_f16 v[54:57], v[200:203], v[176:179], 0
	v_mfma_f32_16x16x32_f16 v[46:49], v[192:195], v[184:187], 0
	v_mfma_f32_16x16x32_f16 v[38:41], v[200:203], v[184:187], 0
	v_mfma_f32_16x16x32_f16 v[94:97], v[196:199], v[164:167], v[94:97]
	v_mfma_f32_16x16x32_f16 v[86:89], v[204:207], v[164:167], v[86:89]
	v_mfma_f32_16x16x32_f16 v[78:81], v[196:199], v[172:175], v[78:81]
	v_mfma_f32_16x16x32_f16 v[70:73], v[204:207], v[172:175], v[70:73]
	v_mfma_f32_16x16x32_f16 v[62:65], v[196:199], v[180:183], v[62:65]
	v_mfma_f32_16x16x32_f16 v[54:57], v[204:207], v[180:183], v[54:57]
	v_mfma_f32_16x16x32_f16 v[46:49], v[196:199], v[188:191], v[46:49]
	v_mfma_f32_16x16x32_f16 v[38:41], v[204:207], v[188:191], v[38:41]
	s_barrier
	global_load_lds_dwordx4 v[212:213], off
	v_lshl_add_u64 v[220:221], s[46:47], 0, v[134:135]
	s_add_i32 m0, s44, 0x2000
	s_nop 0
	global_load_lds_dwordx4 v[220:221], off
	s_mov_b32 m0, s65
	v_lshl_add_u64 v[222:223], s[48:49], 0, v[130:131]
	ds_read_b128 v[156:159], v163 offset:16384
	ds_read_b128 v[164:167], v163 offset:17408
	ds_read_b128 v[168:171], v163 offset:18432
	ds_read_b128 v[172:175], v163 offset:19456
	ds_read_b128 v[176:179], v163 offset:20480
	ds_read_b128 v[180:183], v163 offset:21504
	ds_read_b128 v[184:187], v163 offset:22528
	ds_read_b128 v[188:191], v163 offset:23552
	global_load_lds_dwordx4 v[222:223], off
	v_lshl_add_u64 v[224:225], s[48:49], 0, v[132:133]
	s_mov_b32 m0, s68
	s_nop 0
	global_load_lds_dwordx4 v[224:225], off
	s_add_u32 s44, s46, 0x10000
	s_addc_u32 s45, s47, 0
	s_add_i32 s66, s78, s62
	v_lshl_add_u64 v[232:233], s[44:45], 0, v[0:1]
	s_mov_b32 m0, s66
	s_nop 0
	global_load_lds_dwordx4 v[232:233], off
	v_lshl_add_u64 v[232:233], s[44:45], 0, v[134:135]
	s_add_i32 m0, s66, 0x2000
	s_nop 0
	global_load_lds_dwordx4 v[232:233], off
	s_waitcnt vmcnt(8) lgkmcnt(0)
	s_barrier
	v_mfma_f32_16x16x32_f16 v[90:93], v[140:143], v[156:159], 0
	v_mfma_f32_16x16x32_f16 v[82:85], v[148:151], v[156:159], 0
	v_mfma_f32_16x16x32_f16 v[74:77], v[140:143], v[168:171], 0
	v_mfma_f32_16x16x32_f16 v[66:69], v[148:151], v[168:171], 0
	v_mfma_f32_16x16x32_f16 v[58:61], v[140:143], v[176:179], 0
	v_mfma_f32_16x16x32_f16 v[50:53], v[148:151], v[176:179], 0
	v_mfma_f32_16x16x32_f16 v[42:45], v[140:143], v[184:187], 0
	v_mfma_f32_16x16x32_f16 v[34:37], v[148:151], v[184:187], 0
	v_mfma_f32_16x16x32_f16 v[90:93], v[144:147], v[164:167], v[90:93]
	v_mfma_f32_16x16x32_f16 v[82:85], v[152:155], v[164:167], v[82:85]
	v_mfma_f32_16x16x32_f16 v[74:77], v[144:147], v[172:175], v[74:77]
	v_mfma_f32_16x16x32_f16 v[66:69], v[152:155], v[172:175], v[66:69]
	v_mfma_f32_16x16x32_f16 v[58:61], v[144:147], v[180:183], v[58:61]
	v_mfma_f32_16x16x32_f16 v[50:53], v[152:155], v[180:183], v[50:53]
	v_mfma_f32_16x16x32_f16 v[42:45], v[144:147], v[188:191], v[42:45]
	v_mfma_f32_16x16x32_f16 v[34:37], v[152:155], v[188:191], v[34:37]
	v_mfma_f32_16x16x32_f16 v[30:33], v[192:195], v[156:159], 0
	v_mfma_f32_16x16x32_f16 v[26:29], v[200:203], v[156:159], 0
	v_mfma_f32_16x16x32_f16 v[22:25], v[192:195], v[168:171], 0
	v_mfma_f32_16x16x32_f16 v[18:21], v[200:203], v[168:171], 0
	v_mfma_f32_16x16x32_f16 v[14:17], v[192:195], v[176:179], 0
	v_mfma_f32_16x16x32_f16 v[10:13], v[200:203], v[176:179], 0
	v_mfma_f32_16x16x32_f16 v[6:9], v[192:195], v[184:187], 0
	v_mfma_f32_16x16x32_f16 v[2:5], v[200:203], v[184:187], 0
	v_mfma_f32_16x16x32_f16 v[30:33], v[196:199], v[164:167], v[30:33]
	v_mfma_f32_16x16x32_f16 v[26:29], v[204:207], v[164:167], v[26:29]
	v_mfma_f32_16x16x32_f16 v[22:25], v[196:199], v[172:175], v[22:25]
	v_mfma_f32_16x16x32_f16 v[18:21], v[204:207], v[172:175], v[18:21]
	v_mfma_f32_16x16x32_f16 v[14:17], v[196:199], v[180:183], v[14:17]
	v_mfma_f32_16x16x32_f16 v[10:13], v[204:207], v[180:183], v[10:13]
	v_mfma_f32_16x16x32_f16 v[6:9], v[196:199], v[188:191], v[6:9]
	v_mfma_f32_16x16x32_f16 v[2:5], v[204:207], v[188:191], v[2:5]
	s_barrier
; #define PG8_STAGE(bufoff, gbase, voff) do { _Pragma("unroll") for (int _i = 0; _i < 2; ++_i) \
;         __builtin_amdgcn_global_load_lds((const unsigned*)((const char*)(gbase) + (voff)[_i]), (LAS unsigned*)(lds + (bufoff) + ldsw + _i * 8192), 16, 0, 0); } while (0)
; #define PG8_LDA(dst, b, h) do { _Pragma("unroll") for (int m = 0; m < 4; ++m) _Pragma("unroll") for (int k = 0; k < 2; ++k) dst[m][k] = *(const LAS h16x8*)(lds + PG8_SA(b, h) + aoff + m * 2048 + k * 1024); } while (0)
; #define PG8_LDB(dst, b, h) do { _Pragma("unroll") for (int n = 0; n < 2; ++n) _Pragma("unroll") for (int k = 0; k < 2; ++k) dst[n][k] = *(const LAS h16x8*)(lds + PG8_SB(b, h) + boff + n * 2048 + k * 1024); } while (0)
; #define PG8_MMA(ai, bj, At, Bt_) do { __builtin_amdgcn_s_setprio(1); _Pragma("unroll") for (int m = 0; m < 4; ++m) _Pragma("unroll") for (int n = 0; n < 2; ++n) _Pragma("unroll") for (int k = 0; k < 2; ++k) \
;         acc[ai][bj][m][n] = __builtin_amdgcn_mfma_f32_16x16x32_f16(Bt_[n][k], At[m][k], acc[ai][bj][m][n], 0, 0, 0); __builtin_amdgcn_s_setprio(0); } while (0)
; #define PG8_WAIT_V(n) asm volatile("s_waitcnt vmcnt(" #n ")" ::: "memory")
; #define PG8_WAIT_L(n) asm volatile("s_waitcnt lgkmcnt(" #n ")" ::: "memory")
; #define PG8_BAR __builtin_amdgcn_s_barrier()
; #define PG8_SCHED __builtin_amdgcn_sched_barrier(0)
; template <class Epi, class AMap>
; __device__ __forceinline__ void gemm_phase(LAS unsigned char* lds, const AMap am, const int lda, const h16* Bt, const int ldb, const int M, const int N, const int K, const Epi& E) {
;     ...
;             PG8_LDB(B0, 1, 0); PG8_SCHED; PG8_LDA(At, 1, 0); PG8_STAGE(PG8_SA(0, 1), a2 + hstepA, voffA);
;             PG8_WAIT_L(8); PG8_BAR; PG8_WAIT_L(0); PG8_MMA(0, 0, At, B0); PG8_BAR; PG8_SCHED;
;             PG8_LDB(B1, 1, 1); PG8_STAGE(PG8_SB(1, 0), b3, voffB);
;             PG8_BAR; PG8_WAIT_L(0); PG8_MMA(0, 1, At, B1); PG8_BAR;
;             PG8_LDA(At, 1, 1); PG8_STAGE(PG8_SA(1, 0), a3, voffA);
;             PG8_BAR; PG8_WAIT_L(0); PG8_MMA(1, 0, At, B0); PG8_BAR; PG8_SCHED;
;             PG8_STAGE(PG8_SB(1, 1), b3 + hstepB, voffB);
;             PG8_WAIT_V(6); PG8_BAR; PG8_MMA(1, 1, At, B1); PG8_BAR;
	s_add_i32 s66, 0, 0x18000
	v_add_u32_e32 v234, s66, v161
	ds_read_b128 v[140:143], v234
	ds_read_b128 v[144:147], v234 offset:1024
	ds_read_b128 v[148:151], v234 offset:2048
	ds_read_b128 v[152:155], v234 offset:3072
	s_add_u32 s44, s48, 0x1c0000
	s_addc_u32 s45, s49, 0
	s_mov_b32 m0, s69
	v_lshl_add_u64 v[232:233], s[44:45], 0, v[130:131]
	ds_read_b128 v[156:159], v163 offset:32768
	ds_read_b128 v[164:167], v163 offset:33792
	ds_read_b128 v[168:171], v163 offset:34816
	ds_read_b128 v[172:175], v163 offset:35840
	ds_read_b128 v[176:179], v163 offset:36864
	ds_read_b128 v[180:183], v163 offset:37888
	ds_read_b128 v[184:187], v163 offset:38912
	ds_read_b128 v[188:191], v163 offset:39936
	global_load_lds_dwordx4 v[232:233], off
	v_lshl_add_u64 v[232:233], s[44:45], 0, v[132:133]
	s_mov_b32 m0, s70
	s_nop 0
	global_load_lds_dwordx4 v[232:233], off
	s_waitcnt lgkmcnt(11)
	s_add_i32 s48, 0, 0x1c000
	s_add_i32 s44, s66, s62
	v_add_u32_e32 v234, s48, v161
	v_lshl_add_u64 v[212:213], v[212:213], 0, s[92:93]
	s_mov_b32 m0, s44
	ds_read_b128 v[192:195], v234
	ds_read_b128 v[196:199], v234 offset:1024
	ds_read_b128 v[200:203], v234 offset:2048
	ds_read_b128 v[204:207], v234 offset:3072
	s_waitcnt vmcnt(8) lgkmcnt(0)
	s_barrier
	v_mfma_f32_16x16x32_f16 v[126:129], v[140:143], v[156:159], v[126:129]
	v_mfma_f32_16x16x32_f16 v[122:125], v[148:151], v[156:159], v[122:125]
	v_mfma_f32_16x16x32_f16 v[118:121], v[140:143], v[168:171], v[118:121]
	v_mfma_f32_16x16x32_f16 v[114:117], v[148:151], v[168:171], v[114:117]
	v_mfma_f32_16x16x32_f16 v[110:113], v[140:143], v[176:179], v[110:113]
	v_mfma_f32_16x16x32_f16 v[106:109], v[148:151], v[176:179], v[106:109]
	v_mfma_f32_16x16x32_f16 v[102:105], v[140:143], v[184:187], v[102:105]
	v_mfma_f32_16x16x32_f16 v[98:101], v[148:151], v[184:187], v[98:101]
	v_mfma_f32_16x16x32_f16 v[126:129], v[144:147], v[164:167], v[126:129]
	v_mfma_f32_16x16x32_f16 v[122:125], v[152:155], v[164:167], v[122:125]
	v_mfma_f32_16x16x32_f16 v[118:121], v[144:147], v[172:175], v[118:121]
	v_mfma_f32_16x16x32_f16 v[114:117], v[152:155], v[172:175], v[114:117]
	v_mfma_f32_16x16x32_f16 v[110:113], v[144:147], v[180:183], v[110:113]
	v_mfma_f32_16x16x32_f16 v[106:109], v[152:155], v[180:183], v[106:109]
	v_mfma_f32_16x16x32_f16 v[102:105], v[144:147], v[188:191], v[102:105]
	v_mfma_f32_16x16x32_f16 v[98:101], v[152:155], v[188:191], v[98:101]
	v_mfma_f32_16x16x32_f16 v[94:97], v[192:195], v[156:159], v[94:97]
	v_mfma_f32_16x16x32_f16 v[86:89], v[200:203], v[156:159], v[86:89]
	v_mfma_f32_16x16x32_f16 v[78:81], v[192:195], v[168:171], v[78:81]
	v_mfma_f32_16x16x32_f16 v[70:73], v[200:203], v[168:171], v[70:73]
	v_mfma_f32_16x16x32_f16 v[62:65], v[192:195], v[176:179], v[62:65]
	v_mfma_f32_16x16x32_f16 v[54:57], v[200:203], v[176:179], v[54:57]
	v_mfma_f32_16x16x32_f16 v[46:49], v[192:195], v[184:187], v[46:49]
	v_mfma_f32_16x16x32_f16 v[38:41], v[200:203], v[184:187], v[38:41]
	v_mfma_f32_16x16x32_f16 v[94:97], v[196:199], v[164:167], v[94:97]
	v_mfma_f32_16x16x32_f16 v[86:89], v[204:207], v[164:167], v[86:89]
	v_mfma_f32_16x16x32_f16 v[78:81], v[196:199], v[172:175], v[78:81]
	v_mfma_f32_16x16x32_f16 v[70:73], v[204:207], v[172:175], v[70:73]
	v_mfma_f32_16x16x32_f16 v[62:65], v[196:199], v[180:183], v[62:65]
	v_mfma_f32_16x16x32_f16 v[54:57], v[204:207], v[180:183], v[54:57]
	v_mfma_f32_16x16x32_f16 v[46:49], v[196:199], v[188:191], v[46:49]
	v_mfma_f32_16x16x32_f16 v[38:41], v[204:207], v[188:191], v[38:41]
	s_barrier
	global_load_lds_dwordx4 v[212:213], off
	v_lshl_add_u64 v[212:213], v[220:221], 0, s[92:93]
	s_add_i32 m0, s44, 0x2000
	s_nop 0
	global_load_lds_dwordx4 v[212:213], off
	s_mov_b32 m0, s71
	v_lshl_add_u64 v[212:213], v[222:223], 0, s[92:93]
	ds_read_b128 v[156:159], v163 offset:49152
	ds_read_b128 v[164:167], v163 offset:50176
	ds_read_b128 v[168:171], v163 offset:51200
	ds_read_b128 v[172:175], v163 offset:52224
	ds_read_b128 v[176:179], v163 offset:53248
	ds_read_b128 v[180:183], v163 offset:54272
	ds_read_b128 v[184:187], v163 offset:55296
	ds_read_b128 v[188:191], v163 offset:56320
	global_load_lds_dwordx4 v[212:213], off
	v_lshl_add_u64 v[212:213], v[224:225], 0, s[92:93]
	s_mov_b32 m0, s72
	s_nop 0
	global_load_lds_dwordx4 v[212:213], off
	s_add_u32 s44, s46, 0x10080
	s_addc_u32 s45, s47, 0
	s_add_i32 s46, s48, s62
	v_lshl_add_u64 v[232:233], s[44:45], 0, v[0:1]
	s_mov_b32 m0, s46
	s_nop 0
	global_load_lds_dwordx4 v[232:233], off
	v_lshl_add_u64 v[232:233], s[44:45], 0, v[134:135]
	s_add_i32 m0, s46, 0x2000
	s_nop 0
	global_load_lds_dwordx4 v[232:233], off
	s_add_u32 s27, s27, 0x100
	s_addc_u32 s29, s29, 0
	s_cmp_ge_i32 s60, s24
	s_mov_b64 s[44:45], s[0:1]
	s_mov_b32 s46, s60
	s_waitcnt vmcnt(8) lgkmcnt(0)
	s_barrier
	v_mfma_f32_16x16x32_f16 v[90:93], v[140:143], v[156:159], v[90:93]
	v_mfma_f32_16x16x32_f16 v[82:85], v[148:151], v[156:159], v[82:85]
	v_mfma_f32_16x16x32_f16 v[74:77], v[140:143], v[168:171], v[74:77]
	v_mfma_f32_16x16x32_f16 v[66:69], v[148:151], v[168:171], v[66:69]
	v_mfma_f32_16x16x32_f16 v[58:61], v[140:143], v[176:179], v[58:61]
	v_mfma_f32_16x16x32_f16 v[50:53], v[148:151], v[176:179], v[50:53]
	v_mfma_f32_16x16x32_f16 v[42:45], v[140:143], v[184:187], v[42:45]
	v_mfma_f32_16x16x32_f16 v[34:37], v[148:151], v[184:187], v[34:37]
	v_mfma_f32_16x16x32_f16 v[90:93], v[144:147], v[164:167], v[90:93]
	v_mfma_f32_16x16x32_f16 v[82:85], v[152:155], v[164:167], v[82:85]
	v_mfma_f32_16x16x32_f16 v[74:77], v[144:147], v[172:175], v[74:77]
	v_mfma_f32_16x16x32_f16 v[66:69], v[152:155], v[172:175], v[66:69]
	v_mfma_f32_16x16x32_f16 v[58:61], v[144:147], v[180:183], v[58:61]
	v_mfma_f32_16x16x32_f16 v[50:53], v[152:155], v[180:183], v[50:53]
	v_mfma_f32_16x16x32_f16 v[42:45], v[144:147], v[188:191], v[42:45]
	v_mfma_f32_16x16x32_f16 v[34:37], v[152:155], v[188:191], v[34:37]
	v_mfma_f32_16x16x32_f16 v[30:33], v[192:195], v[156:159], v[30:33]
	v_mfma_f32_16x16x32_f16 v[26:29], v[200:203], v[156:159], v[26:29]
	v_mfma_f32_16x16x32_f16 v[22:25], v[192:195], v[168:171], v[22:25]
	v_mfma_f32_16x16x32_f16 v[18:21], v[200:203], v[168:171], v[18:21]
	v_mfma_f32_16x16x32_f16 v[14:17], v[192:195], v[176:179], v[14:17]
	v_mfma_f32_16x16x32_f16 v[10:13], v[200:203], v[176:179], v[10:13]
	v_mfma_f32_16x16x32_f16 v[6:9], v[192:195], v[184:187], v[6:9]
	v_mfma_f32_16x16x32_f16 v[2:5], v[200:203], v[184:187], v[2:5]
	v_mfma_f32_16x16x32_f16 v[30:33], v[196:199], v[164:167], v[30:33]
	v_mfma_f32_16x16x32_f16 v[26:29], v[204:207], v[164:167], v[26:29]
	v_mfma_f32_16x16x32_f16 v[22:25], v[196:199], v[172:175], v[22:25]
	v_mfma_f32_16x16x32_f16 v[18:21], v[204:207], v[172:175], v[18:21]
	v_mfma_f32_16x16x32_f16 v[14:17], v[196:199], v[180:183], v[14:17]
	v_mfma_f32_16x16x32_f16 v[10:13], v[204:207], v[180:183], v[10:13]
	v_mfma_f32_16x16x32_f16 v[6:9], v[196:199], v[188:191], v[6:9]
	v_mfma_f32_16x16x32_f16 v[2:5], v[204:207], v[188:191], v[2:5]
	s_barrier
	s_cbranch_scc1 .Lg4x_667

; #define PG8_WAIT_V(n) asm volatile("s_waitcnt vmcnt(" #n ")" ::: "memory")
; #define PG8_BAR __builtin_amdgcn_s_barrier()
; template <class Epi, class AMap>
; __device__ __forceinline__ void gemm_phase(LAS unsigned char* lds, const AMap am, const int lda, const h16* Bt, const int ldb, const int M, const int N, const int K, const Epi& E) {
;     ...
;         E(acc, cur, wr, wc, fr, fq);
;         if (!has_next) break;
; #pragma unroll
;         for (int a = 0; a < 2; ++a)
; #pragma unroll
;             for (int b = 0; b < 2; ++b)
; #pragma unroll
;                 for (int m = 0; m < 4; ++m)
; #pragma unroll
;                     for (int n = 0; n < 2; ++n) acc[a][b][m][n] = (f32x4){0.f, 0.f, 0.f, 0.f};
;         cur = nxt; cA = nA; cB = nB; ++ui;
;     }
;     PG8_WAIT_V(0);
;     if (wr == 0) PG8_BAR;
.Lg4x_667:
	s_cmpk_gt_u32 s50, 0xff
	s_cbranch_scc1 .Lgx6
	s_barrier

; #define PG8_STAGE(bufoff, gbase, voff) do { _Pragma("unroll") for (int _i = 0; _i < 2; ++_i) \
;         __builtin_amdgcn_global_load_lds((const unsigned*)((const char*)(gbase) + (voff)[_i]), (LAS unsigned*)(lds + (bufoff) + ldsw + _i * 8192), 16, 0, 0); } while (0)
; #define PG8_LDA(dst, b, h) do { _Pragma("unroll") for (int m = 0; m < 4; ++m) _Pragma("unroll") for (int k = 0; k < 2; ++k) dst[m][k] = *(const LAS h16x8*)(lds + PG8_SA(b, h) + aoff + m * 2048 + k * 1024); } while (0)
; #define PG8_LDB(dst, b, h) do { _Pragma("unroll") for (int n = 0; n < 2; ++n) _Pragma("unroll") for (int k = 0; k < 2; ++k) dst[n][k] = *(const LAS h16x8*)(lds + PG8_SB(b, h) + boff + n * 2048 + k * 1024); } while (0)
; #define PG8_MMA(ai, bj, At, Bt_) do { __builtin_amdgcn_s_setprio(1); _Pragma("unroll") for (int m = 0; m < 4; ++m) _Pragma("unroll") for (int n = 0; n < 2; ++n) _Pragma("unroll") for (int k = 0; k < 2; ++k) \
;         acc[ai][bj][m][n] = __builtin_amdgcn_mfma_f32_16x16x32_f16(Bt_[n][k], At[m][k], acc[ai][bj][m][n], 0, 0, 0); __builtin_amdgcn_s_setprio(0); } while (0)
; template <class Epi, class AMap>
; __device__ __forceinline__ void gemm_phase(LAS unsigned char* lds, const AMap am, const int lda, const h16* Bt, const int ldb, const int M, const int N, const int K, const Epi& E) {
;     ...
;         const bool has_next = S.next(ui + 1, nxt);
;         const char* nA = has_next ? am(nxt.pn) + (size_t)nxt.pm * tstepA : cA; const char* nB = has_next ? (const char*)Bt + (size_t)nxt.pn * tstepB : cB;
; #pragma unroll 1
;         for (int t = 0; t < nt; t += 2) {
;             const bool last = (t == nt - 2);
;             const char* a1 = cA + (size_t)(t + 1) * kstep;
;             const char* a2 = last ? nA : cA + (size_t)(t + 2) * kstep; const char* b2 = last ? nB : cB + (size_t)(t + 2) * kstep;
;             const char* a3 = a2 + kstep; const char* b3 = b2 + kstep;
;             PG8_LDB(B0, 0, 0); PG8_SCHED; PG8_LDA(At, 0, 0); PG8_STAGE(PG8_SA(1, 1), a1 + hstepA, voffA);
;             PG8_WAIT_L(8); PG8_BAR; PG8_WAIT_L(0); PG8_MMA(0, 0, At, B0); PG8_BAR; PG8_SCHED;
;             PG8_LDB(B1, 0, 1); PG8_STAGE(PG8_SB(0, 0), b2, voffB);
;             PG8_BAR; PG8_WAIT_L(0); PG8_MMA(0, 1, At, B1); PG8_BAR;
;             PG8_LDA(At, 0, 1); PG8_STAGE(PG8_SA(0, 0), a2, voffA);
;             PG8_BAR; PG8_WAIT_L(0); PG8_MMA(1, 0, At, B0); PG8_BAR; PG8_SCHED;
.Lg4p_692:
	s_add_i32 s51, s26, 2
	s_add_u32 s0, s22, 0x100
	s_addc_u32 s1, s23, 0
	s_add_i32 s60, 0, 0x10000
	v_add_u32_e32 v234, s60, v175
	ds_read_b128 v[82:85], v234
	ds_read_b128 v[86:89], v234 offset:1024
	ds_read_b128 v[138:141], v234 offset:2048
	ds_read_b128 v[142:145], v234 offset:3072
	s_cmp_eq_u32 s61, s26
	s_cselect_b32 s26, s21, s29
	s_cselect_b32 s49, s47, s1
	s_cselect_b32 s48, s46, s0
	s_cselect_b32 s27, s20, s45
	v_lshl_add_u64 v[172:173], s[22:23], 0, v[152:153]
	s_add_i32 m0, s74, 0xc000
	ds_read_b128 v[156:159], v177
	ds_read_b128 v[160:163], v177 offset:1024
	ds_read_b128 v[164:167], v177 offset:2048
	ds_read_b128 v[168:171], v177 offset:3072
	ds_read_b128 v[178:181], v177 offset:4096
	ds_read_b128 v[182:185], v177 offset:5120
	ds_read_b128 v[186:189], v177 offset:6144
	ds_read_b128 v[190:193], v177 offset:7168
	global_load_lds_dwordx4 v[172:173], off
	v_lshl_add_u64 v[172:173], s[22:23], 0, v[154:155]
	s_add_i32 m0, s74, 0xe000
	s_nop 0
	global_load_lds_dwordx4 v[172:173], off
	s_waitcnt lgkmcnt(11)
	s_add_i32 s62, 0, 0x14000
	v_add_u32_e32 v172, s62, v175
	s_add_i32 s22, s60, s71
	ds_read_b128 v[194:197], v172
	ds_read_b128 v[198:201], v172 offset:1024
	ds_read_b128 v[202:205], v172 offset:2048
	ds_read_b128 v[220:223], v172 offset:3072
	s_waitcnt vmcnt(60) lgkmcnt(0)
	s_barrier
	v_mfma_f32_16x16x32_f16 v[134:137], v[82:85], v[156:159], 0
	v_mfma_f32_16x16x32_f16 v[130:133], v[138:141], v[156:159], 0
	v_mfma_f32_16x16x32_f16 v[126:129], v[82:85], v[164:167], 0
	v_mfma_f32_16x16x32_f16 v[122:125], v[138:141], v[164:167], 0
	v_mfma_f32_16x16x32_f16 v[118:121], v[82:85], v[178:181], 0
	v_mfma_f32_16x16x32_f16 v[114:117], v[138:141], v[178:181], 0
	v_mfma_f32_16x16x32_f16 v[110:113], v[82:85], v[186:189], 0
	v_mfma_f32_16x16x32_f16 v[106:109], v[138:141], v[186:189], 0
	v_mfma_f32_16x16x32_f16 v[134:137], v[86:89], v[160:163], v[134:137]
	v_mfma_f32_16x16x32_f16 v[130:133], v[142:145], v[160:163], v[130:133]
	v_mfma_f32_16x16x32_f16 v[126:129], v[86:89], v[168:171], v[126:129]
	v_mfma_f32_16x16x32_f16 v[122:125], v[142:145], v[168:171], v[122:125]
	v_mfma_f32_16x16x32_f16 v[118:121], v[86:89], v[182:185], v[118:121]
	v_mfma_f32_16x16x32_f16 v[114:117], v[142:145], v[182:185], v[114:117]
	v_mfma_f32_16x16x32_f16 v[110:113], v[86:89], v[190:193], v[110:113]
	v_mfma_f32_16x16x32_f16 v[106:109], v[142:145], v[190:193], v[106:109]
	v_mfma_f32_16x16x32_f16 v[62:65], v[194:197], v[156:159], 0
	v_mfma_f32_16x16x32_f16 v[58:61], v[202:205], v[156:159], 0
	v_mfma_f32_16x16x32_f16 v[54:57], v[194:197], v[164:167], 0
	v_mfma_f32_16x16x32_f16 v[50:53], v[202:205], v[164:167], 0
	v_mfma_f32_16x16x32_f16 v[46:49], v[194:197], v[178:181], 0
	v_mfma_f32_16x16x32_f16 v[42:45], v[202:205], v[178:181], 0
	v_mfma_f32_16x16x32_f16 v[38:41], v[194:197], v[186:189], 0
	v_mfma_f32_16x16x32_f16 v[34:37], v[202:205], v[186:189], 0
	v_mfma_f32_16x16x32_f16 v[62:65], v[198:201], v[160:163], v[62:65]
	v_mfma_f32_16x16x32_f16 v[58:61], v[220:223], v[160:163], v[58:61]
	v_mfma_f32_16x16x32_f16 v[54:57], v[198:201], v[168:171], v[54:57]
	v_mfma_f32_16x16x32_f16 v[50:53], v[220:223], v[168:171], v[50:53]
	v_mfma_f32_16x16x32_f16 v[46:49], v[198:201], v[182:185], v[46:49]
	v_mfma_f32_16x16x32_f16 v[42:45], v[220:223], v[182:185], v[42:45]
	v_mfma_f32_16x16x32_f16 v[38:41], v[198:201], v[190:193], v[38:41]
	v_mfma_f32_16x16x32_f16 v[34:37], v[220:223], v[190:193], v[34:37]
	s_barrier
	v_lshl_add_u64 v[172:173], s[26:27], 0, v[0:1]
	s_mov_b32 m0, s22
	v_lshl_add_u64 v[206:207], s[26:27], 0, v[150:151]
	global_load_lds_dwordx4 v[172:173], off
	s_add_i32 m0, s22, 0x2000
	s_nop 0
	global_load_lds_dwordx4 v[206:207], off
	s_mov_b32 m0, s74
	v_lshl_add_u64 v[212:213], s[48:49], 0, v[146:147]
	ds_read_b128 v[156:159], v177 offset:16384
	ds_read_b128 v[160:163], v177 offset:17408
	ds_read_b128 v[164:167], v177 offset:18432
	ds_read_b128 v[168:171], v177 offset:19456
	ds_read_b128 v[178:181], v177 offset:20480
	ds_read_b128 v[182:185], v177 offset:21504
	ds_read_b128 v[186:189], v177 offset:22528
	ds_read_b128 v[190:193], v177 offset:23552
	global_load_lds_dwordx4 v[212:213], off
	v_lshl_add_u64 v[224:225], s[48:49], 0, v[148:149]
	s_mov_b32 m0, s75
	s_nop 0
	global_load_lds_dwordx4 v[224:225], off
	s_add_u32 s22, s26, 0x10000
	s_addc_u32 s23, s27, 0
	s_add_i32 s60, s62, s71
	v_lshl_add_u64 v[232:233], s[22:23], 0, v[0:1]
	s_mov_b32 m0, s60
	s_nop 0
	global_load_lds_dwordx4 v[232:233], off
	v_lshl_add_u64 v[232:233], s[22:23], 0, v[150:151]
	s_add_i32 m0, s60, 0x2000
	s_nop 0
	global_load_lds_dwordx4 v[232:233], off
	s_waitcnt vmcnt(8) lgkmcnt(0)
	s_barrier
; #define PG8_STAGE(bufoff, gbase, voff) do { _Pragma("unroll") for (int _i = 0; _i < 2; ++_i) \
;         __builtin_amdgcn_global_load_lds((const unsigned*)((const char*)(gbase) + (voff)[_i]), (LAS unsigned*)(lds + (bufoff) + ldsw + _i * 8192), 16, 0, 0); } while (0)
; #define PG8_LDA(dst, b, h) do { _Pragma("unroll") for (int m = 0; m < 4; ++m) _Pragma("unroll") for (int k = 0; k < 2; ++k) dst[m][k] = *(const LAS h16x8*)(lds + PG8_SA(b, h) + aoff + m * 2048 + k * 1024); } while (0)
; #define PG8_LDB(dst, b, h) do { _Pragma("unroll") for (int n = 0; n < 2; ++n) _Pragma("unroll") for (int k = 0; k < 2; ++k) dst[n][k] = *(const LAS h16x8*)(lds + PG8_SB(b, h) + boff + n * 2048 + k * 1024); } while (0)
; #define PG8_MMA(ai, bj, At, Bt_) do { __builtin_amdgcn_s_setprio(1); _Pragma("unroll") for (int m = 0; m < 4; ++m) _Pragma("unroll") for (int n = 0; n < 2; ++n) _Pragma("unroll") for (int k = 0; k < 2; ++k) \
;         acc[ai][bj][m][n] = __builtin_amdgcn_mfma_f32_16x16x32_f16(Bt_[n][k], At[m][k], acc[ai][bj][m][n], 0, 0, 0); __builtin_amdgcn_s_setprio(0); } while (0)
; #define PG8_WAIT_V(n) asm volatile("s_waitcnt vmcnt(" #n ")" ::: "memory")
; #define PG8_WAIT_L(n) asm volatile("s_waitcnt lgkmcnt(" #n ")" ::: "memory")
; #define PG8_BAR __builtin_amdgcn_s_barrier()
; #define PG8_SCHED __builtin_amdgcn_sched_barrier(0)
; template <class Epi, class AMap>
; __device__ __forceinline__ void gemm_phase(LAS unsigned char* lds, const AMap am, const int lda, const h16* Bt, const int ldb, const int M, const int N, const int K, const Epi& E) {
;     ...
;             PG8_BAR; PG8_WAIT_L(0); PG8_MMA(1, 0, At, B0); PG8_BAR; PG8_SCHED;
;             PG8_STAGE(PG8_SB(0, 1), b2 + hstepB, voffB);
;             PG8_WAIT_V(6); PG8_BAR; PG8_MMA(1, 1, At, B1); PG8_BAR;
;             PG8_LDB(B0, 1, 0); PG8_SCHED; PG8_LDA(At, 1, 0); PG8_STAGE(PG8_SA(0, 1), a2 + hstepA, voffA);
;             PG8_WAIT_L(8); PG8_BAR; PG8_WAIT_L(0); PG8_MMA(0, 0, At, B0); PG8_BAR; PG8_SCHED;
;             PG8_LDB(B1, 1, 1); PG8_STAGE(PG8_SB(1, 0), b3, voffB);
;             PG8_BAR; PG8_WAIT_L(0); PG8_MMA(0, 1, At, B1); PG8_BAR;
	v_mfma_f32_16x16x32_f16 v[102:105], v[82:85], v[156:159], 0
	v_mfma_f32_16x16x32_f16 v[98:101], v[138:141], v[156:159], 0
	v_mfma_f32_16x16x32_f16 v[94:97], v[82:85], v[164:167], 0
	v_mfma_f32_16x16x32_f16 v[90:93], v[138:141], v[164:167], 0
	v_mfma_f32_16x16x32_f16 v[78:81], v[82:85], v[178:181], 0
	v_mfma_f32_16x16x32_f16 v[74:77], v[138:141], v[178:181], 0
	v_mfma_f32_16x16x32_f16 v[70:73], v[82:85], v[186:189], 0
	v_mfma_f32_16x16x32_f16 v[66:69], v[138:141], v[186:189], 0
	v_mfma_f32_16x16x32_f16 v[102:105], v[86:89], v[160:163], v[102:105]
	v_mfma_f32_16x16x32_f16 v[98:101], v[142:145], v[160:163], v[98:101]
	v_mfma_f32_16x16x32_f16 v[94:97], v[86:89], v[168:171], v[94:97]
	v_mfma_f32_16x16x32_f16 v[90:93], v[142:145], v[168:171], v[90:93]
	v_mfma_f32_16x16x32_f16 v[78:81], v[86:89], v[182:185], v[78:81]
	v_mfma_f32_16x16x32_f16 v[74:77], v[142:145], v[182:185], v[74:77]
	v_mfma_f32_16x16x32_f16 v[70:73], v[86:89], v[190:193], v[70:73]
	v_mfma_f32_16x16x32_f16 v[66:69], v[142:145], v[190:193], v[66:69]
	v_mfma_f32_16x16x32_f16 v[30:33], v[194:197], v[156:159], 0
	v_mfma_f32_16x16x32_f16 v[26:29], v[202:205], v[156:159], 0
	v_mfma_f32_16x16x32_f16 v[22:25], v[194:197], v[164:167], 0
	v_mfma_f32_16x16x32_f16 v[18:21], v[202:205], v[164:167], 0
	v_mfma_f32_16x16x32_f16 v[14:17], v[194:197], v[178:181], 0
	v_mfma_f32_16x16x32_f16 v[10:13], v[202:205], v[178:181], 0
	v_mfma_f32_16x16x32_f16 v[6:9], v[194:197], v[186:189], 0
	v_mfma_f32_16x16x32_f16 v[2:5], v[202:205], v[186:189], 0
	v_mfma_f32_16x16x32_f16 v[30:33], v[198:201], v[160:163], v[30:33]
	v_mfma_f32_16x16x32_f16 v[26:29], v[220:223], v[160:163], v[26:29]
	v_mfma_f32_16x16x32_f16 v[22:25], v[198:201], v[168:171], v[22:25]
	v_mfma_f32_16x16x32_f16 v[18:21], v[220:223], v[168:171], v[18:21]
	v_mfma_f32_16x16x32_f16 v[14:17], v[198:201], v[182:185], v[14:17]
	v_mfma_f32_16x16x32_f16 v[10:13], v[220:223], v[182:185], v[10:13]
	v_mfma_f32_16x16x32_f16 v[6:9], v[198:201], v[190:193], v[6:9]
	v_mfma_f32_16x16x32_f16 v[2:5], v[220:223], v[190:193], v[2:5]
	s_barrier
	s_add_i32 s60, 0, 0x18000
	v_add_u32_e32 v234, s60, v175
	ds_read_b128 v[82:85], v234
	ds_read_b128 v[86:89], v234 offset:1024
	ds_read_b128 v[138:141], v234 offset:2048
	ds_read_b128 v[142:145], v234 offset:3072
	s_add_u32 s22, s48, 0x1c0000
	s_addc_u32 s23, s49, 0
	s_mov_b32 m0, s76
	v_lshl_add_u64 v[232:233], s[22:23], 0, v[146:147]
	ds_read_b128 v[156:159], v177 offset:32768
	ds_read_b128 v[160:163], v177 offset:33792
	ds_read_b128 v[164:167], v177 offset:34816
	ds_read_b128 v[168:171], v177 offset:35840
	ds_read_b128 v[178:181], v177 offset:36864
	ds_read_b128 v[182:185], v177 offset:37888
	ds_read_b128 v[186:189], v177 offset:38912
	ds_read_b128 v[190:193], v177 offset:39936
	global_load_lds_dwordx4 v[232:233], off
	v_lshl_add_u64 v[232:233], s[22:23], 0, v[148:149]
	s_mov_b32 m0, s77
	s_nop 0
	global_load_lds_dwordx4 v[232:233], off
	s_waitcnt lgkmcnt(11)
	s_add_i32 s48, 0, 0x1c000
	s_add_i32 s22, s60, s71
	v_add_u32_e32 v214, s48, v175
	v_lshl_add_u64 v[172:173], v[172:173], 0, s[92:93]
	s_mov_b32 m0, s22
	ds_read_b128 v[194:197], v214
	ds_read_b128 v[198:201], v214 offset:1024
	ds_read_b128 v[202:205], v214 offset:2048
	ds_read_b128 v[220:223], v214 offset:3072
	s_waitcnt vmcnt(8) lgkmcnt(0)
	s_barrier
	v_mfma_f32_16x16x32_f16 v[134:137], v[82:85], v[156:159], v[134:137]
	v_mfma_f32_16x16x32_f16 v[130:133], v[138:141], v[156:159], v[130:133]
	v_mfma_f32_16x16x32_f16 v[126:129], v[82:85], v[164:167], v[126:129]
	v_mfma_f32_16x16x32_f16 v[122:125], v[138:141], v[164:167], v[122:125]
	v_mfma_f32_16x16x32_f16 v[118:121], v[82:85], v[178:181], v[118:121]
	v_mfma_f32_16x16x32_f16 v[114:117], v[138:141], v[178:181], v[114:117]
	v_mfma_f32_16x16x32_f16 v[110:113], v[82:85], v[186:189], v[110:113]
	v_mfma_f32_16x16x32_f16 v[106:109], v[138:141], v[186:189], v[106:109]
	v_mfma_f32_16x16x32_f16 v[134:137], v[86:89], v[160:163], v[134:137]
	v_mfma_f32_16x16x32_f16 v[130:133], v[142:145], v[160:163], v[130:133]
	v_mfma_f32_16x16x32_f16 v[126:129], v[86:89], v[168:171], v[126:129]
	v_mfma_f32_16x16x32_f16 v[122:125], v[142:145], v[168:171], v[122:125]
	v_mfma_f32_16x16x32_f16 v[118:121], v[86:89], v[182:185], v[118:121]
	v_mfma_f32_16x16x32_f16 v[114:117], v[142:145], v[182:185], v[114:117]
	v_mfma_f32_16x16x32_f16 v[110:113], v[86:89], v[190:193], v[110:113]
	v_mfma_f32_16x16x32_f16 v[106:109], v[142:145], v[190:193], v[106:109]
	v_mfma_f32_16x16x32_f16 v[62:65], v[194:197], v[156:159], v[62:65]
	v_mfma_f32_16x16x32_f16 v[58:61], v[202:205], v[156:159], v[58:61]
	v_mfma_f32_16x16x32_f16 v[54:57], v[194:197], v[164:167], v[54:57]
	v_mfma_f32_16x16x32_f16 v[50:53], v[202:205], v[164:167], v[50:53]
	v_mfma_f32_16x16x32_f16 v[46:49], v[194:197], v[178:181], v[46:49]
	v_mfma_f32_16x16x32_f16 v[42:45], v[202:205], v[178:181], v[42:45]
	v_mfma_f32_16x16x32_f16 v[38:41], v[194:197], v[186:189], v[38:41]
	v_mfma_f32_16x16x32_f16 v[34:37], v[202:205], v[186:189], v[34:37]
	v_mfma_f32_16x16x32_f16 v[62:65], v[198:201], v[160:163], v[62:65]
	v_mfma_f32_16x16x32_f16 v[58:61], v[220:223], v[160:163], v[58:61]
	v_mfma_f32_16x16x32_f16 v[54:57], v[198:201], v[168:171], v[54:57]
	v_mfma_f32_16x16x32_f16 v[50:53], v[220:223], v[168:171], v[50:53]
	v_mfma_f32_16x16x32_f16 v[46:49], v[198:201], v[182:185], v[46:49]
	v_mfma_f32_16x16x32_f16 v[42:45], v[220:223], v[182:185], v[42:45]
	v_mfma_f32_16x16x32_f16 v[38:41], v[198:201], v[190:193], v[38:41]
	v_mfma_f32_16x16x32_f16 v[34:37], v[220:223], v[190:193], v[34:37]
	s_barrier
; #define PG8_STAGE(bufoff, gbase, voff) do { _Pragma("unroll") for (int _i = 0; _i < 2; ++_i) \
;         __builtin_amdgcn_global_load_lds((const unsigned*)((const char*)(gbase) + (voff)[_i]), (LAS unsigned*)(lds + (bufoff) + ldsw + _i * 8192), 16, 0, 0); } while (0)
; #define PG8_LDA(dst, b, h) do { _Pragma("unroll") for (int m = 0; m < 4; ++m) _Pragma("unroll") for (int k = 0; k < 2; ++k) dst[m][k] = *(const LAS h16x8*)(lds + PG8_SA(b, h) + aoff + m * 2048 + k * 1024); } while (0)
; #define PG8_LDB(dst, b, h) do { _Pragma("unroll") for (int n = 0; n < 2; ++n) _Pragma("unroll") for (int k = 0; k < 2; ++k) dst[n][k] = *(const LAS h16x8*)(lds + PG8_SB(b, h) + boff + n * 2048 + k * 1024); } while (0)
; #define PG8_MMA(ai, bj, At, Bt_) do { __builtin_amdgcn_s_setprio(1); _Pragma("unroll") for (int m = 0; m < 4; ++m) _Pragma("unroll") for (int n = 0; n < 2; ++n) _Pragma("unroll") for (int k = 0; k < 2; ++k) \
;         acc[ai][bj][m][n] = __builtin_amdgcn_mfma_f32_16x16x32_f16(Bt_[n][k], At[m][k], acc[ai][bj][m][n], 0, 0, 0); __builtin_amdgcn_s_setprio(0); } while (0)
; #define PG8_WAIT_V(n) asm volatile("s_waitcnt vmcnt(" #n ")" ::: "memory")
; #define PG8_WAIT_L(n) asm volatile("s_waitcnt lgkmcnt(" #n ")" ::: "memory")
; #define PG8_BAR __builtin_amdgcn_s_barrier()
; #define PG8_SCHED __builtin_amdgcn_sched_barrier(0)
; template <class Epi, class AMap>
; __device__ __forceinline__ void gemm_phase(LAS unsigned char* lds, const AMap am, const int lda, const h16* Bt, const int ldb, const int M, const int N, const int K, const Epi& E) {
;     ...
;             PG8_LDB(B1, 1, 1); PG8_STAGE(PG8_SB(1, 0), b3, voffB);
;             PG8_BAR; PG8_WAIT_L(0); PG8_MMA(0, 1, At, B1); PG8_BAR;
;             PG8_LDA(At, 1, 1); PG8_STAGE(PG8_SA(1, 0), a3, voffA);
;             PG8_BAR; PG8_WAIT_L(0); PG8_MMA(1, 0, At, B0); PG8_BAR; PG8_SCHED;
;             PG8_STAGE(PG8_SB(1, 1), b3 + hstepB, voffB);
;             PG8_WAIT_V(6); PG8_BAR; PG8_MMA(1, 1, At, B1); PG8_BAR;
	global_load_lds_dwordx4 v[172:173], off
	v_lshl_add_u64 v[172:173], v[206:207], 0, s[92:93]
	s_add_i32 m0, s22, 0x2000
	s_nop 0
	global_load_lds_dwordx4 v[172:173], off
	s_mov_b32 m0, s79
	v_lshl_add_u64 v[172:173], v[212:213], 0, s[92:93]
	ds_read_b128 v[156:159], v177 offset:49152
	ds_read_b128 v[160:163], v177 offset:50176
	ds_read_b128 v[164:167], v177 offset:51200
	ds_read_b128 v[168:171], v177 offset:52224
	ds_read_b128 v[178:181], v177 offset:53248
	ds_read_b128 v[182:185], v177 offset:54272
	ds_read_b128 v[186:189], v177 offset:55296
	ds_read_b128 v[190:193], v177 offset:56320
	global_load_lds_dwordx4 v[172:173], off
	v_lshl_add_u64 v[172:173], v[224:225], 0, s[92:93]
	s_mov_b32 m0, s80
	s_nop 0
	global_load_lds_dwordx4 v[172:173], off
	s_add_u32 s22, s26, 0x10080
	s_addc_u32 s23, s27, 0
	s_add_i32 s26, s48, s71
	v_lshl_add_u64 v[232:233], s[22:23], 0, v[0:1]
	s_mov_b32 m0, s26
	s_nop 0
	global_load_lds_dwordx4 v[232:233], off
	v_lshl_add_u64 v[232:233], s[22:23], 0, v[150:151]
	s_add_i32 m0, s26, 0x2000
	s_nop 0
	global_load_lds_dwordx4 v[232:233], off
	s_add_u32 s29, s29, 0x100
	s_addc_u32 s45, s45, 0
	s_cmp_ge_i32 s51, s24
	s_mov_b64 s[22:23], s[0:1]
	s_mov_b32 s26, s51
	s_waitcnt vmcnt(8) lgkmcnt(0)
	s_barrier
	v_mfma_f32_16x16x32_f16 v[102:105], v[82:85], v[156:159], v[102:105]
	v_mfma_f32_16x16x32_f16 v[98:101], v[138:141], v[156:159], v[98:101]
	v_mfma_f32_16x16x32_f16 v[94:97], v[82:85], v[164:167], v[94:97]
	v_mfma_f32_16x16x32_f16 v[90:93], v[138:141], v[164:167], v[90:93]
	v_mfma_f32_16x16x32_f16 v[78:81], v[82:85], v[178:181], v[78:81]
	v_mfma_f32_16x16x32_f16 v[74:77], v[138:141], v[178:181], v[74:77]
	v_mfma_f32_16x16x32_f16 v[70:73], v[82:85], v[186:189], v[70:73]
	v_mfma_f32_16x16x32_f16 v[66:69], v[138:141], v[186:189], v[66:69]
	v_mfma_f32_16x16x32_f16 v[102:105], v[86:89], v[160:163], v[102:105]
	v_mfma_f32_16x16x32_f16 v[98:101], v[142:145], v[160:163], v[98:101]
	v_mfma_f32_16x16x32_f16 v[94:97], v[86:89], v[168:171], v[94:97]
	v_mfma_f32_16x16x32_f16 v[90:93], v[142:145], v[168:171], v[90:93]
	v_mfma_f32_16x16x32_f16 v[78:81], v[86:89], v[182:185], v[78:81]
	v_mfma_f32_16x16x32_f16 v[74:77], v[142:145], v[182:185], v[74:77]
	v_mfma_f32_16x16x32_f16 v[70:73], v[86:89], v[190:193], v[70:73]
	v_mfma_f32_16x16x32_f16 v[66:69], v[142:145], v[190:193], v[66:69]
	v_mfma_f32_16x16x32_f16 v[30:33], v[194:197], v[156:159], v[30:33]
	v_mfma_f32_16x16x32_f16 v[26:29], v[202:205], v[156:159], v[26:29]
	v_mfma_f32_16x16x32_f16 v[22:25], v[194:197], v[164:167], v[22:25]
	v_mfma_f32_16x16x32_f16 v[18:21], v[202:205], v[164:167], v[18:21]
	v_mfma_f32_16x16x32_f16 v[14:17], v[194:197], v[178:181], v[14:17]
	v_mfma_f32_16x16x32_f16 v[10:13], v[202:205], v[178:181], v[10:13]
	v_mfma_f32_16x16x32_f16 v[6:9], v[194:197], v[186:189], v[6:9]
	v_mfma_f32_16x16x32_f16 v[2:5], v[202:205], v[186:189], v[2:5]
	v_mfma_f32_16x16x32_f16 v[30:33], v[198:201], v[160:163], v[30:33]
	v_mfma_f32_16x16x32_f16 v[26:29], v[220:223], v[160:163], v[26:29]
	v_mfma_f32_16x16x32_f16 v[22:25], v[198:201], v[168:171], v[22:25]
	v_mfma_f32_16x16x32_f16 v[18:21], v[220:223], v[168:171], v[18:21]
	v_mfma_f32_16x16x32_f16 v[14:17], v[198:201], v[182:185], v[14:17]
	v_mfma_f32_16x16x32_f16 v[10:13], v[220:223], v[182:185], v[10:13]
	v_mfma_f32_16x16x32_f16 v[6:9], v[198:201], v[190:193], v[6:9]
	v_mfma_f32_16x16x32_f16 v[2:5], v[220:223], v[190:193], v[2:5]
	s_barrier
	s_cbranch_scc1 .Lg4x_692
